# P4 and P7 int8 GEMM epilogues: hoist per-row-group scale loads, drop serialized vmcnt(0) waits
# speedup vs baseline: 1.0023x; 1.0023x over previous
; #define PG8_STAGE(bufoff, gbase, voff) do { _Pragma("unroll") for (int _i = 0; _i < 2; ++_i) \
;         __builtin_amdgcn_global_load_lds((const unsigned*)((const char*)(gbase) + (voff)[_i]), (LAS unsigned*)(lds + (bufoff) + ldsw + _i * 8192), 16, 0, 0); } while (0)
; #define PG8_LDA(dst, b, h) do { _Pragma("unroll") for (int m = 0; m < 4; ++m) _Pragma("unroll") for (int k = 0; k < 2; ++k) dst[m][k] = *(const LAS bf16x8*)(lds + PG8_SA(b, h) + aoff + m * 2048 + k * 1024); } while (0)
; #define PG8_WAIT_V(n) asm volatile("s_waitcnt vmcnt(" #n ")" ::: "memory")
; #define PG8_WAIT_L(n) asm volatile("s_waitcnt lgkmcnt(" #n ")" ::: "memory")
; template <class Epi, class Sched>
; __device__ __forceinline__ void gemm_phase(LAS unsigned char* lds, const Gemm g, const Sched& S, const Epi& E) {
;     ...
;         for (int t = 0; t < nt; t += 2) {
;             const bool last = (t == nt - 2);
;             const char* a1 = cA + (size_t)(t + 1) * kstep;
;             const char* a2 = last ? nA : cA + (size_t)(t + 2) * kstep; const char* b2 = last ? nB : cB + (size_t)(t + 2) * kstep;
;             const char* a3 = a2 + kstep; const char* b3 = b2 + kstep;
;             PG8_LDB(B0, 0, 0); PG8_SCHED; PG8_LDA(At, 0, 0); PG8_STAGE(PG8_SA(1, 1), a1 + hstepA, voffA);
;             PG8_WAIT_L(8); PG8_BAR; PG8_WAIT_L(0); PG8_MMA(0, 0, At, B0); PG8_BAR; PG8_SCHED;
;             PG8_LDB(B1, 0, 1); PG8_STAGE(PG8_SB(0, 0), b2, voffB);
;             PG8_BAR; PG8_WAIT_L(0); PG8_MMA(0, 1, At, B1); PG8_BAR;
;             PG8_LDA(At, 0, 1); PG8_STAGE(PG8_SA(0, 0), a2, voffA);
;             PG8_BAR; PG8_WAIT_L(0); PG8_MMA(1, 0, At, B0); PG8_BAR; PG8_SCHED;
;             PG8_STAGE(PG8_SB(0, 1), b2 + hstepB, voffB);
;             PG8_WAIT_V(6); PG8_BAR; PG8_MMA(1, 1, At, B1); PG8_BAR;
;             PG8_LDB(B0, 1, 0); PG8_SCHED; PG8_LDA(At, 1, 0); PG8_STAGE(PG8_SA(0, 1), a2 + hstepA, voffA);
;             PG8_WAIT_L(8); PG8_BAR; PG8_WAIT_L(0); PG8_MMA(0, 0, At, B0); PG8_BAR; PG8_SCHED;
;             PG8_LDB(B1, 1, 1); PG8_STAGE(PG8_SB(1, 0), b3, voffB);
;             PG8_BAR; PG8_WAIT_L(0); PG8_MMA(0, 1, At, B1); PG8_BAR;
;             PG8_LDA(At, 1, 1); PG8_STAGE(PG8_SA(1, 0), a3, voffA);
;             PG8_BAR; PG8_WAIT_L(0); PG8_MMA(1, 0, At, B0); PG8_BAR; PG8_SCHED;
;             PG8_STAGE(PG8_SB(1, 1), b3 + hstepB, voffB);
;             PG8_WAIT_V(6); PG8_BAR; PG8_MMA(1, 1, At, B1); PG8_BAR;
.LBB0_386:
	ds_read_b128 v[104:107], v169
	ds_read_b128 v[108:111], v169 offset:1024
	ds_read_b128 v[112:115], v169 offset:2048
	ds_read_b128 v[116:119], v169 offset:3072
	s_add_u32 s24, s22, 0xfff80080
	s_addc_u32 s25, s23, -1
	s_cmp_eq_u32 s48, 12
	s_cselect_b32 s27, s15, s25
	s_cselect_b32 s26, s44, s24
	s_cselect_b32 s25, s13, s47
	s_cselect_b32 s24, s45, s46
	v_lshl_add_u64 v[164:165], s[22:23], 0, v[152:153]
	s_add_i32 m0, s21, 0xc000
	ds_read_b128 v[160:163], v170
	ds_read_b128 v[172:175], v170 offset:1024
	ds_read_b128 v[178:181], v170 offset:2048
	ds_read_b128 v[182:185], v170 offset:3072
	ds_read_b128 v[186:189], v170 offset:4096
	ds_read_b128 v[190:193], v170 offset:5120
	ds_read_b128 v[194:197], v170 offset:6144
	ds_read_b128 v[198:201], v170 offset:7168
	global_load_lds_dwordx4 v[164:165], off
	v_lshl_add_u64 v[164:165], s[22:23], 0, v[154:155]
	s_add_i32 m0, s21, 0xe000
	s_nop 0
	global_load_lds_dwordx4 v[164:165], off
	s_waitcnt lgkmcnt(8)
	s_barrier
	s_waitcnt lgkmcnt(0)
	s_setprio 1
	s_waitcnt lgkmcnt(0)
	v_mfma_i32_16x16x64_i8 v[140:143], v[104:107], v[160:163], v[140:143]
	v_mfma_i32_16x16x64_i8 v[136:139], v[112:115], v[160:163], v[136:139]
	v_mfma_i32_16x16x64_i8 v[124:127], v[104:107], v[178:181], v[124:127]
	v_mfma_i32_16x16x64_i8 v[120:123], v[112:115], v[178:181], v[120:123]
	v_mfma_i32_16x16x64_i8 v[92:95], v[104:107], v[186:189], v[92:95]
	v_mfma_i32_16x16x64_i8 v[88:91], v[112:115], v[186:189], v[88:91]
	v_mfma_i32_16x16x64_i8 v[76:79], v[104:107], v[194:197], v[76:79]
	v_mfma_i32_16x16x64_i8 v[72:75], v[112:115], v[194:197], v[72:75]
	v_mfma_i32_16x16x64_i8 v[140:143], v[108:111], v[172:175], v[140:143]
	v_mfma_i32_16x16x64_i8 v[136:139], v[116:119], v[172:175], v[136:139]
	v_mfma_i32_16x16x64_i8 v[124:127], v[108:111], v[182:185], v[124:127]
	v_mfma_i32_16x16x64_i8 v[120:123], v[116:119], v[182:185], v[120:123]
	v_mfma_i32_16x16x64_i8 v[92:95], v[108:111], v[190:193], v[92:95]
	v_mfma_i32_16x16x64_i8 v[88:91], v[116:119], v[190:193], v[88:91]
	v_mfma_i32_16x16x64_i8 v[76:79], v[108:111], v[198:201], v[76:79]
	v_mfma_i32_16x16x64_i8 v[72:75], v[116:119], v[198:201], v[72:75]
	s_setprio 0
	s_barrier
	s_add_i32 s49, s40, s29
	v_lshl_add_u64 v[164:165], s[24:25], 0, v[148:149]
	s_mov_b32 m0, s49
	ds_read_b128 v[202:205], v171
	ds_read_b128 v[206:209], v171 offset:1024
	ds_read_b128 v[210:213], v171 offset:2048
	ds_read_b128 v[214:217], v171 offset:3072
	global_load_lds_dwordx4 v[164:165], off
	v_lshl_add_u64 v[218:219], s[24:25], 0, v[144:145]
	s_add_i32 m0, s49, 0x2000
	s_nop 0
	global_load_lds_dwordx4 v[218:219], off
	s_barrier
	s_waitcnt lgkmcnt(0)
	s_setprio 1
	s_waitcnt lgkmcnt(0)
	v_mfma_i32_16x16x64_i8 v[132:135], v[202:205], v[160:163], v[132:135]
	v_mfma_i32_16x16x64_i8 v[128:131], v[210:213], v[160:163], v[128:131]
	v_mfma_i32_16x16x64_i8 v[100:103], v[202:205], v[178:181], v[100:103]
	v_mfma_i32_16x16x64_i8 v[96:99], v[210:213], v[178:181], v[96:99]
	v_mfma_i32_16x16x64_i8 v[84:87], v[202:205], v[186:189], v[84:87]
	v_mfma_i32_16x16x64_i8 v[80:83], v[210:213], v[186:189], v[80:83]
	v_mfma_i32_16x16x64_i8 v[68:71], v[202:205], v[194:197], v[68:71]
	v_mfma_i32_16x16x64_i8 v[64:67], v[210:213], v[194:197], v[64:67]
	v_mfma_i32_16x16x64_i8 v[132:135], v[206:209], v[172:175], v[132:135]
	v_mfma_i32_16x16x64_i8 v[128:131], v[214:217], v[172:175], v[128:131]
	v_mfma_i32_16x16x64_i8 v[100:103], v[206:209], v[182:185], v[100:103]
	v_mfma_i32_16x16x64_i8 v[96:99], v[214:217], v[182:185], v[96:99]
	v_mfma_i32_16x16x64_i8 v[84:87], v[206:209], v[190:193], v[84:87]
	v_mfma_i32_16x16x64_i8 v[80:83], v[214:217], v[190:193], v[80:83]
	v_mfma_i32_16x16x64_i8 v[68:71], v[206:209], v[198:201], v[68:71]
	v_mfma_i32_16x16x64_i8 v[64:67], v[214:217], v[198:201], v[64:67]
	s_setprio 0
	s_mov_b32 m0, s21
	v_lshl_add_u64 v[220:221], s[26:27], 0, v[150:151]
	s_barrier
	ds_read_b128 v[160:163], v170 offset:16384
	ds_read_b128 v[172:175], v170 offset:17408
	ds_read_b128 v[178:181], v170 offset:18432
	ds_read_b128 v[182:185], v170 offset:19456
	ds_read_b128 v[186:189], v170 offset:20480
	ds_read_b128 v[190:193], v170 offset:21504
	ds_read_b128 v[194:197], v170 offset:22528
	ds_read_b128 v[198:201], v170 offset:23552
	global_load_lds_dwordx4 v[220:221], off
	v_lshl_add_u64 v[222:223], s[26:27], 0, v[146:147]
	s_mov_b32 m0, s33
	s_nop 0
	global_load_lds_dwordx4 v[222:223], off
	s_barrier
	s_waitcnt lgkmcnt(0)
	s_setprio 1
	s_waitcnt lgkmcnt(0)
	v_mfma_i32_16x16x64_i8 v[60:63], v[104:107], v[160:163], v[60:63]
	v_mfma_i32_16x16x64_i8 v[56:59], v[112:115], v[160:163], v[56:59]
	v_mfma_i32_16x16x64_i8 v[44:47], v[104:107], v[178:181], v[44:47]
	v_mfma_i32_16x16x64_i8 v[40:43], v[112:115], v[178:181], v[40:43]
	v_mfma_i32_16x16x64_i8 v[28:31], v[104:107], v[186:189], v[28:31]
	v_mfma_i32_16x16x64_i8 v[24:27], v[112:115], v[186:189], v[24:27]
	v_mfma_i32_16x16x64_i8 v[12:15], v[104:107], v[194:197], v[12:15]
	v_mfma_i32_16x16x64_i8 v[8:11], v[112:115], v[194:197], v[8:11]
	v_mfma_i32_16x16x64_i8 v[60:63], v[108:111], v[172:175], v[60:63]
	v_mfma_i32_16x16x64_i8 v[56:59], v[116:119], v[172:175], v[56:59]
	v_mfma_i32_16x16x64_i8 v[44:47], v[108:111], v[182:185], v[44:47]
	v_mfma_i32_16x16x64_i8 v[40:43], v[116:119], v[182:185], v[40:43]
	v_mfma_i32_16x16x64_i8 v[28:31], v[108:111], v[190:193], v[28:31]
	v_mfma_i32_16x16x64_i8 v[24:27], v[116:119], v[190:193], v[24:27]
	v_mfma_i32_16x16x64_i8 v[12:15], v[108:111], v[198:201], v[12:15]
	v_mfma_i32_16x16x64_i8 v[8:11], v[116:119], v[198:201], v[8:11]
	s_setprio 0
	s_barrier
; #define PG8_STAGE(bufoff, gbase, voff) do { _Pragma("unroll") for (int _i = 0; _i < 2; ++_i) \
;         __builtin_amdgcn_global_load_lds((const unsigned*)((const char*)(gbase) + (voff)[_i]), (LAS unsigned*)(lds + (bufoff) + ldsw + _i * 8192), 16, 0, 0); } while (0)
; #define PG8_LDA(dst, b, h) do { _Pragma("unroll") for (int m = 0; m < 4; ++m) _Pragma("unroll") for (int k = 0; k < 2; ++k) dst[m][k] = *(const LAS bf16x8*)(lds + PG8_SA(b, h) + aoff + m * 2048 + k * 1024); } while (0)
; #define PG8_LDB(dst, b, h) do { _Pragma("unroll") for (int n = 0; n < 2; ++n) _Pragma("unroll") for (int k = 0; k < 2; ++k) dst[n][k] = *(const LAS bf16x8*)(lds + PG8_SB(b, h) + boff + n * 2048 + k * 1024); } while (0)
; #define PG8_WAIT_V(n) asm volatile("s_waitcnt vmcnt(" #n ")" ::: "memory")
; #define PG8_WAIT_L(n) asm volatile("s_waitcnt lgkmcnt(" #n ")" ::: "memory")
; #define PG8_BAR __builtin_amdgcn_s_barrier()
; #define PG8_SCHED __builtin_amdgcn_sched_barrier(0)
; template <class Epi, class Sched>
; __device__ __forceinline__ void gemm_phase(LAS unsigned char* lds, const Gemm g, const Sched& S, const Epi& E) {
;     ...
;             PG8_LDB(B0, 0, 0); PG8_SCHED; PG8_LDA(At, 0, 0); PG8_STAGE(PG8_SA(1, 1), a1 + hstepA, voffA);
;             PG8_WAIT_L(8); PG8_BAR; PG8_WAIT_L(0); PG8_MMA(0, 0, At, B0); PG8_BAR; PG8_SCHED;
;             PG8_LDB(B1, 0, 1); PG8_STAGE(PG8_SB(0, 0), b2, voffB);
;             PG8_BAR; PG8_WAIT_L(0); PG8_MMA(0, 1, At, B1); PG8_BAR;
;             PG8_LDA(At, 0, 1); PG8_STAGE(PG8_SA(0, 0), a2, voffA);
;             PG8_BAR; PG8_WAIT_L(0); PG8_MMA(1, 0, At, B0); PG8_BAR; PG8_SCHED;
;             PG8_STAGE(PG8_SB(0, 1), b2 + hstepB, voffB);
;             PG8_WAIT_V(6); PG8_BAR; PG8_MMA(1, 1, At, B1); PG8_BAR;
;             PG8_LDB(B0, 1, 0); PG8_SCHED; PG8_LDA(At, 1, 0); PG8_STAGE(PG8_SA(0, 1), a2 + hstepA, voffA);
;             PG8_WAIT_L(8); PG8_BAR; PG8_WAIT_L(0); PG8_MMA(0, 0, At, B0); PG8_BAR; PG8_SCHED;
;             PG8_LDB(B1, 1, 1); PG8_STAGE(PG8_SB(1, 0), b3, voffB);
;             PG8_BAR; PG8_WAIT_L(0); PG8_MMA(0, 1, At, B1); PG8_BAR;
;             PG8_LDA(At, 1, 1); PG8_STAGE(PG8_SA(1, 0), a3, voffA);
;             PG8_BAR; PG8_WAIT_L(0); PG8_MMA(1, 0, At, B0); PG8_BAR; PG8_SCHED;
;             PG8_STAGE(PG8_SB(1, 1), b3 + hstepB, voffB);
;             PG8_WAIT_V(6); PG8_BAR; PG8_MMA(1, 1, At, B1); PG8_BAR;
	s_add_u32 s50, s24, 0x40000
	s_addc_u32 s51, s25, 0
	s_add_i32 s49, s41, s29
	v_lshl_add_u64 v[104:105], s[50:51], 0, v[148:149]
	s_mov_b32 m0, s49
	s_nop 0
	global_load_lds_dwordx4 v[104:105], off
	v_lshl_add_u64 v[104:105], s[50:51], 0, v[144:145]
	s_add_i32 m0, s49, 0x2000
	s_nop 0
	global_load_lds_dwordx4 v[104:105], off
	s_waitcnt vmcnt(6)
	s_barrier
	s_setprio 1
	v_mfma_i32_16x16x64_i8 v[52:55], v[202:205], v[160:163], v[52:55]
	v_mfma_i32_16x16x64_i8 v[48:51], v[210:213], v[160:163], v[48:51]
	v_mfma_i32_16x16x64_i8 v[36:39], v[202:205], v[178:181], v[36:39]
	v_mfma_i32_16x16x64_i8 v[32:35], v[210:213], v[178:181], v[32:35]
	v_mfma_i32_16x16x64_i8 v[20:23], v[202:205], v[186:189], v[20:23]
	v_mfma_i32_16x16x64_i8 v[16:19], v[210:213], v[186:189], v[16:19]
	v_mfma_i32_16x16x64_i8 v[4:7], v[202:205], v[194:197], v[4:7]
	v_mfma_i32_16x16x64_i8 v[0:3], v[210:213], v[194:197], v[0:3]
	v_mfma_i32_16x16x64_i8 v[52:55], v[206:209], v[172:175], v[52:55]
	v_mfma_i32_16x16x64_i8 v[48:51], v[214:217], v[172:175], v[48:51]
	v_mfma_i32_16x16x64_i8 v[36:39], v[206:209], v[182:185], v[36:39]
	v_mfma_i32_16x16x64_i8 v[32:35], v[214:217], v[182:185], v[32:35]
	v_mfma_i32_16x16x64_i8 v[20:23], v[206:209], v[190:193], v[20:23]
	v_mfma_i32_16x16x64_i8 v[16:19], v[214:217], v[190:193], v[16:19]
	v_mfma_i32_16x16x64_i8 v[4:7], v[206:209], v[198:201], v[4:7]
	v_mfma_i32_16x16x64_i8 v[0:3], v[214:217], v[198:201], v[0:3]
	s_setprio 0
	s_add_i32 s49, 0, 0x18000
	v_add_u32_e32 v116, s49, v167
	s_barrier
	ds_read_b128 v[104:107], v116
	ds_read_b128 v[108:111], v116 offset:1024
	ds_read_b128 v[112:115], v116 offset:2048
	ds_read_b128 v[116:119], v116 offset:3072
	s_add_u32 s26, s26, 0x80000
	s_addc_u32 s27, s27, 0
	s_mov_b32 m0, s34
	v_lshl_add_u64 v[202:203], s[26:27], 0, v[150:151]
	ds_read_b128 v[160:163], v170 offset:32768
	ds_read_b128 v[172:175], v170 offset:33792
	ds_read_b128 v[178:181], v170 offset:34816
	ds_read_b128 v[182:185], v170 offset:35840
	ds_read_b128 v[186:189], v170 offset:36864
	ds_read_b128 v[190:193], v170 offset:37888
	ds_read_b128 v[194:197], v170 offset:38912
	ds_read_b128 v[198:201], v170 offset:39936
	global_load_lds_dwordx4 v[202:203], off
	v_lshl_add_u64 v[202:203], s[26:27], 0, v[146:147]
	s_mov_b32 m0, s35
	s_nop 0
	global_load_lds_dwordx4 v[202:203], off
	s_waitcnt lgkmcnt(8)
	s_barrier
	s_waitcnt lgkmcnt(0)
	s_setprio 1
	s_waitcnt lgkmcnt(0)
	v_mfma_i32_16x16x64_i8 v[140:143], v[104:107], v[160:163], v[140:143]
	v_mfma_i32_16x16x64_i8 v[136:139], v[112:115], v[160:163], v[136:139]
	v_mfma_i32_16x16x64_i8 v[124:127], v[104:107], v[178:181], v[124:127]
	v_mfma_i32_16x16x64_i8 v[120:123], v[112:115], v[178:181], v[120:123]
	v_mfma_i32_16x16x64_i8 v[92:95], v[104:107], v[186:189], v[92:95]
	v_mfma_i32_16x16x64_i8 v[88:91], v[112:115], v[186:189], v[88:91]
	v_mfma_i32_16x16x64_i8 v[76:79], v[104:107], v[194:197], v[76:79]
	v_mfma_i32_16x16x64_i8 v[72:75], v[112:115], v[194:197], v[72:75]
	v_mfma_i32_16x16x64_i8 v[140:143], v[108:111], v[172:175], v[140:143]
	v_mfma_i32_16x16x64_i8 v[136:139], v[116:119], v[172:175], v[136:139]
	v_mfma_i32_16x16x64_i8 v[124:127], v[108:111], v[182:185], v[124:127]
	v_mfma_i32_16x16x64_i8 v[120:123], v[116:119], v[182:185], v[120:123]
	v_mfma_i32_16x16x64_i8 v[92:95], v[108:111], v[190:193], v[92:95]
	v_mfma_i32_16x16x64_i8 v[88:91], v[116:119], v[190:193], v[88:91]
	v_mfma_i32_16x16x64_i8 v[76:79], v[108:111], v[198:201], v[76:79]
	v_mfma_i32_16x16x64_i8 v[72:75], v[116:119], v[198:201], v[72:75]
	s_setprio 0
	s_barrier
	s_add_i32 s26, 0, 0x1c000
	s_add_i32 s27, s49, s29
	v_add_u32_e32 v214, s26, v167
	v_lshl_add_u64 v[164:165], v[164:165], 0, s[6:7]
	s_mov_b32 m0, s27
	ds_read_b128 v[202:205], v214
	ds_read_b128 v[206:209], v214 offset:1024
	ds_read_b128 v[210:213], v214 offset:2048
	ds_read_b128 v[214:217], v214 offset:3072
	global_load_lds_dwordx4 v[164:165], off
	v_lshl_add_u64 v[164:165], v[218:219], 0, s[6:7]
	s_add_i32 m0, s27, 0x2000
	s_nop 0
	global_load_lds_dwordx4 v[164:165], off
	s_barrier
	s_waitcnt lgkmcnt(0)
	s_setprio 1
	s_waitcnt lgkmcnt(0)
	v_mfma_i32_16x16x64_i8 v[132:135], v[202:205], v[160:163], v[132:135]
	v_mfma_i32_16x16x64_i8 v[128:131], v[210:213], v[160:163], v[128:131]
	v_mfma_i32_16x16x64_i8 v[100:103], v[202:205], v[178:181], v[100:103]
	v_mfma_i32_16x16x64_i8 v[96:99], v[210:213], v[178:181], v[96:99]
	v_mfma_i32_16x16x64_i8 v[84:87], v[202:205], v[186:189], v[84:87]
	v_mfma_i32_16x16x64_i8 v[80:83], v[210:213], v[186:189], v[80:83]
	v_mfma_i32_16x16x64_i8 v[68:71], v[202:205], v[194:197], v[68:71]
	v_mfma_i32_16x16x64_i8 v[64:67], v[210:213], v[194:197], v[64:67]
	v_mfma_i32_16x16x64_i8 v[132:135], v[206:209], v[172:175], v[132:135]
	v_mfma_i32_16x16x64_i8 v[128:131], v[214:217], v[172:175], v[128:131]
	v_mfma_i32_16x16x64_i8 v[100:103], v[206:209], v[182:185], v[100:103]
	v_mfma_i32_16x16x64_i8 v[96:99], v[214:217], v[182:185], v[96:99]
	v_mfma_i32_16x16x64_i8 v[84:87], v[206:209], v[190:193], v[84:87]
	v_mfma_i32_16x16x64_i8 v[80:83], v[214:217], v[190:193], v[80:83]
	v_mfma_i32_16x16x64_i8 v[68:71], v[206:209], v[198:201], v[68:71]
	v_mfma_i32_16x16x64_i8 v[64:67], v[214:217], v[198:201], v[64:67]
	s_setprio 0
	s_mov_b32 m0, s37
	v_lshl_add_u64 v[164:165], v[220:221], 0, s[6:7]
	s_barrier
	ds_read_b128 v[160:163], v170 offset:49152
	ds_read_b128 v[172:175], v170 offset:50176
	ds_read_b128 v[178:181], v170 offset:51200
	ds_read_b128 v[182:185], v170 offset:52224
	ds_read_b128 v[186:189], v170 offset:53248
	ds_read_b128 v[190:193], v170 offset:54272
	ds_read_b128 v[194:197], v170 offset:55296
	ds_read_b128 v[198:201], v170 offset:56320
	global_load_lds_dwordx4 v[164:165], off
	v_lshl_add_u64 v[164:165], v[222:223], 0, s[6:7]
	s_mov_b32 m0, s38
	s_nop 0
	global_load_lds_dwordx4 v[164:165], off
	s_barrier
; __device__ __forceinline__ float ld_agent(const float* p) { return __hip_atomic_load(p, __ATOMIC_RELAXED, __HIP_MEMORY_SCOPE_AGENT); }
; #define PG8_STAGE(bufoff, gbase, voff) do { _Pragma("unroll") for (int _i = 0; _i < 2; ++_i) \
;         __builtin_amdgcn_global_load_lds((const unsigned*)((const char*)(gbase) + (voff)[_i]), (LAS unsigned*)(lds + (bufoff) + ldsw + _i * 8192), 16, 0, 0); } while (0)
; #define PG8_LDA(dst, b, h) do { _Pragma("unroll") for (int m = 0; m < 4; ++m) _Pragma("unroll") for (int k = 0; k < 2; ++k) dst[m][k] = *(const LAS bf16x8*)(lds + PG8_SA(b, h) + aoff + m * 2048 + k * 1024); } while (0)
; #define PG8_MMA(ai, bj, At, Bt) do { __builtin_amdgcn_s_setprio(1); _Pragma("unroll") for (int m = 0; m < 4; ++m) _Pragma("unroll") for (int n = 0; n < 2; ++n) _Pragma("unroll") for (int k = 0; k < 2; ++k) \
;         acc[ai][bj][m][n] = MmaOp<Epi::I8>::run(Bt[n][k], At[m][k], acc[ai][bj][m][n]); __builtin_amdgcn_s_setprio(0); } while (0)
; #define PG8_WAIT_V(n) asm volatile("s_waitcnt vmcnt(" #n ")" ::: "memory")
;     __device__ __forceinline__ void operator()(const i32x4 (&acc)[2][2][4][2], const Unit& u, int wr, int wc, int fr_, int fq) const {
;         const int row0 = u.pm * BM + wr * 64 + fr_, col0 = u.pn * BM + wc * 32 + 8 * fq;
;         f32x4 sw[2][2], bv[2][2];
; #pragma unroll
;         for (int bj = 0; bj < 2; ++bj)
; #pragma unroll
;             for (int n = 0; n < 2; ++n) { sw[bj][n] = *(const f32x4*)(swinv + col0 + bj * HALF + 4 * n);
;                 bv[bj][n] = MODE == 1 ? *(const f32x4*)(bias + col0 + bj * HALF + 4 * n) : (f32x4){0.f, 0.f, 0.f, 0.f}; }
; #pragma unroll
;         for (int ai = 0; ai < 2; ++ai)
; #pragma unroll
;             for (int m = 0; m < 4; ++m) {
;                 asm volatile("" ::: "memory");
;                 const int r = row0 + ai * HALF + m * 16; const float rs = ld_agent(fr + r);
; template <class Epi, class Sched>
; __device__ __forceinline__ void gemm_phase(LAS unsigned char* lds, const Gemm g, const Sched& S, const Epi& E) {
;     ...
;             PG8_BAR; PG8_WAIT_L(0); PG8_MMA(0, 1, At, B1); PG8_BAR;
;             PG8_LDA(At, 1, 1); PG8_STAGE(PG8_SA(1, 0), a3, voffA);
;             PG8_BAR; PG8_WAIT_L(0); PG8_MMA(1, 0, At, B0); PG8_BAR; PG8_SCHED;
;             PG8_STAGE(PG8_SB(1, 1), b3 + hstepB, voffB);
;             PG8_WAIT_V(6); PG8_BAR; PG8_MMA(1, 1, At, B1); PG8_BAR;
	s_waitcnt lgkmcnt(0)
	s_setprio 1
	s_waitcnt lgkmcnt(0)
	v_mfma_i32_16x16x64_i8 v[60:63], v[104:107], v[160:163], v[60:63]
	v_mfma_i32_16x16x64_i8 v[56:59], v[112:115], v[160:163], v[56:59]
	v_mfma_i32_16x16x64_i8 v[44:47], v[104:107], v[178:181], v[44:47]
	v_mfma_i32_16x16x64_i8 v[40:43], v[112:115], v[178:181], v[40:43]
	v_mfma_i32_16x16x64_i8 v[28:31], v[104:107], v[186:189], v[28:31]
	v_mfma_i32_16x16x64_i8 v[24:27], v[112:115], v[186:189], v[24:27]
	v_mfma_i32_16x16x64_i8 v[12:15], v[104:107], v[194:197], v[12:15]
	v_mfma_i32_16x16x64_i8 v[8:11], v[112:115], v[194:197], v[8:11]
	v_mfma_i32_16x16x64_i8 v[60:63], v[108:111], v[172:175], v[60:63]
	v_mfma_i32_16x16x64_i8 v[56:59], v[116:119], v[172:175], v[56:59]
	v_mfma_i32_16x16x64_i8 v[44:47], v[108:111], v[182:185], v[44:47]
	v_mfma_i32_16x16x64_i8 v[40:43], v[116:119], v[182:185], v[40:43]
	v_mfma_i32_16x16x64_i8 v[28:31], v[108:111], v[190:193], v[28:31]
	v_mfma_i32_16x16x64_i8 v[24:27], v[116:119], v[190:193], v[24:27]
	v_mfma_i32_16x16x64_i8 v[12:15], v[108:111], v[198:201], v[12:15]
	v_mfma_i32_16x16x64_i8 v[8:11], v[116:119], v[198:201], v[8:11]
	s_setprio 0
	s_barrier
	s_add_u32 s24, s24, 0x40080
	s_addc_u32 s25, s25, 0
	s_add_i32 s26, s26, s29
	v_lshl_add_u64 v[104:105], s[24:25], 0, v[148:149]
	s_mov_b32 m0, s26
	s_nop 0
	global_load_lds_dwordx4 v[104:105], off
	v_lshl_add_u64 v[104:105], s[24:25], 0, v[144:145]
	s_add_i32 m0, s26, 0x2000
	s_nop 0
	global_load_lds_dwordx4 v[104:105], off
	s_waitcnt vmcnt(6)
	s_barrier
	s_setprio 1
	v_mfma_i32_16x16x64_i8 v[52:55], v[202:205], v[160:163], v[52:55]
	v_mfma_i32_16x16x64_i8 v[48:51], v[210:213], v[160:163], v[48:51]
	v_mfma_i32_16x16x64_i8 v[36:39], v[202:205], v[178:181], v[36:39]
	v_mfma_i32_16x16x64_i8 v[32:35], v[210:213], v[178:181], v[32:35]
	v_mfma_i32_16x16x64_i8 v[20:23], v[202:205], v[186:189], v[20:23]
	v_mfma_i32_16x16x64_i8 v[16:19], v[210:213], v[186:189], v[16:19]
	v_mfma_i32_16x16x64_i8 v[4:7], v[202:205], v[194:197], v[4:7]
	v_mfma_i32_16x16x64_i8 v[0:3], v[210:213], v[194:197], v[0:3]
	v_mfma_i32_16x16x64_i8 v[52:55], v[206:209], v[172:175], v[52:55]
	v_mfma_i32_16x16x64_i8 v[48:51], v[214:217], v[172:175], v[48:51]
	v_mfma_i32_16x16x64_i8 v[36:39], v[206:209], v[182:185], v[36:39]
	v_mfma_i32_16x16x64_i8 v[32:35], v[214:217], v[182:185], v[32:35]
	v_mfma_i32_16x16x64_i8 v[20:23], v[206:209], v[190:193], v[20:23]
	v_mfma_i32_16x16x64_i8 v[16:19], v[214:217], v[190:193], v[16:19]
	v_mfma_i32_16x16x64_i8 v[4:7], v[206:209], v[198:201], v[4:7]
	v_mfma_i32_16x16x64_i8 v[0:3], v[214:217], v[198:201], v[0:3]
	s_setprio 0
	s_add_i32 s48, s48, 2
	s_add_u32 s22, s22, 0x100
	s_addc_u32 s23, s23, 0
	s_add_u32 s46, s46, 0x100
	s_addc_u32 s47, s47, 0
	s_cmp_gt_u32 s48, 13
	s_barrier
	s_cbranch_scc0 .LBB0_386
	v_lshl_or_b32 v172, s43, 8, v168
	v_ashrrev_i32_e32 v173, 31, v172
	v_lshl_add_u32 v160, s20, 8, v166
	v_lshl_add_u64 v[108:109], v[172:173], 2, s[8:9]
	v_ashrrev_i32_e32 v161, 31, v160
	global_load_dwordx4 v[112:115], v[108:109], off offset:16
	global_load_dwordx4 v[116:119], v[108:109], off
	global_load_dwordx4 v[104:107], v[108:109], off offset:528
	s_nop 0
	global_load_dwordx4 v[108:111], v[108:109], off offset:512
	v_lshl_add_u64 v[164:165], v[160:161], 2, s[2:3]
	global_load_dword v161, v[164:165], off sc1
	global_load_dword v190, v[164:165], off offset:64 sc1
	global_load_dword v191, v[164:165], off offset:128 sc1
	global_load_dword v192, v[164:165], off offset:192 sc1
	global_load_dword v193, v[164:165], off offset:512 sc1
	global_load_dword v194, v[164:165], off offset:576 sc1
	global_load_dword v195, v[164:165], off offset:640 sc1
	global_load_dword v196, v[164:165], off offset:704 sc1
	v_cvt_f32_i32_e32 v140, v140
	v_cvt_f32_i32_e32 v174, v136
	v_cvt_f32_i32_e32 v141, v141
	v_cvt_f32_i32_e32 v175, v137
	v_cvt_f32_i32_e32 v142, v142
	v_cvt_f32_i32_e32 v178, v138
	v_cvt_f32_i32_e32 v143, v143
	v_cvt_f32_i32_e32 v179, v139
	v_cvt_f32_i32_e32 v132, v132
	v_cvt_f32_i32_e32 v180, v128
	v_cvt_f32_i32_e32 v133, v133
	v_mov_b64_e32 v[162:163], s[54:55]
	v_cvt_f32_i32_e32 v181, v129
	v_cvt_f32_i32_e32 v182, v134
	v_cvt_f32_i32_e32 v183, v130
	v_cvt_f32_i32_e32 v184, v135
	v_cvt_f32_i32_e32 v185, v131
	v_or_b32_e32 v134, 16, v160
	v_mad_i64_i32 v[130:131], s[22:23], v160, s42, v[162:163]
	v_lshlrev_b64 v[128:129], 1, v[172:173]
	v_ashrrev_i32_e32 v135, 31, v134
	v_lshl_add_u64 v[136:137], v[130:131], 0, v[128:129]
	v_lshl_add_u64 v[138:139], v[134:135], 2, s[2:3]
	v_cvt_f32_i32_e32 v124, v124
	v_cvt_f32_i32_e32 v125, v125
	v_cvt_f32_i32_e32 v126, v126
	v_cvt_f32_i32_e32 v122, v122
	v_cvt_f32_i32_e32 v127, v127
	v_cvt_f32_i32_e32 v123, v123
	v_cvt_f32_i32_e32 v98, v98
	v_cvt_f32_i32_e32 v99, v99
	v_cvt_f32_i32_e32 v92, v92
	v_cvt_f32_i32_e32 v93, v93
	v_cvt_f32_i32_e32 v94, v94
	v_cvt_f32_i32_e32 v90, v90
	v_cvt_f32_i32_e32 v95, v95
	v_cvt_f32_i32_e32 v91, v91
	v_cvt_f32_i32_e32 v82, v82
	v_cvt_f32_i32_e32 v83, v83
	v_cvt_f32_i32_e32 v76, v76
	v_cvt_f32_i32_e32 v72, v72
	v_cvt_f32_i32_e32 v77, v77
	v_cvt_f32_i32_e32 v73, v73
	v_cvt_f32_i32_e32 v78, v78
	v_cvt_f32_i32_e32 v74, v74
	v_cvt_f32_i32_e32 v79, v79
	v_cvt_f32_i32_e32 v75, v75
	v_cvt_f32_i32_e32 v70, v70
	v_cvt_f32_i32_e32 v66, v66
	v_cvt_f32_i32_e32 v71, v71
	v_cvt_f32_i32_e32 v67, v67
	v_cvt_f32_i32_e32 v60, v60
	v_cvt_f32_i32_e32 v56, v56
	v_cvt_f32_i32_e32 v61, v61
	v_cvt_f32_i32_e32 v57, v57
	v_cvt_f32_i32_e32 v62, v62
	v_cvt_f32_i32_e32 v58, v58
	v_cvt_f32_i32_e32 v63, v63
	v_cvt_f32_i32_e32 v59, v59
	v_cvt_f32_i32_e32 v54, v54
	v_cvt_f32_i32_e32 v50, v50
	v_cvt_f32_i32_e32 v55, v55
	v_cvt_f32_i32_e32 v51, v51
	v_cvt_f32_i32_e32 v44, v44
	v_cvt_f32_i32_e32 v40, v40
	v_cvt_f32_i32_e32 v45, v45
	v_cvt_f32_i32_e32 v41, v41
	v_cvt_f32_i32_e32 v46, v46
	v_cvt_f32_i32_e32 v42, v42
	v_cvt_f32_i32_e32 v47, v47
	v_cvt_f32_i32_e32 v43, v43
	v_cvt_f32_i32_e32 v38, v38
	v_cvt_f32_i32_e32 v34, v34
	v_cvt_f32_i32_e32 v39, v39
	v_cvt_f32_i32_e32 v35, v35
	v_cvt_f32_i32_e32 v28, v28
	v_cvt_f32_i32_e32 v24, v24
	v_cvt_f32_i32_e32 v29, v29
	s_waitcnt vmcnt(0)
; __device__ __forceinline__ unsigned cvt_pk_bf16(float lo, float hi) { unsigned r; asm volatile("v_cvt_pk_bf16_f32 %0, %1, %2" : "=v"(r) : "v"(lo), "v"(hi)); return r; }
; __device__ __forceinline__ float ld_agent(const float* p) { return __hip_atomic_load(p, __ATOMIC_RELAXED, __HIP_MEMORY_SCOPE_AGENT); }
; __device__ __forceinline__ float sigm(float x) { return __builtin_amdgcn_rcpf(1.f + __builtin_amdgcn_exp2f(-LOG2E * x)); }
;     __device__ __forceinline__ void operator()(const i32x4 (&acc)[2][2][4][2], const Unit& u, int wr, int wc, int fr_, int fq) const {
;     ...
;         for (int ai = 0; ai < 2; ++ai)
; #pragma unroll
;             for (int m = 0; m < 4; ++m) {
;                 asm volatile("" ::: "memory");
;                 const int r = row0 + ai * HALF + m * 16; const float rs = ld_agent(fr + r);
;                 bf16_t* rowp = O + (size_t)r * ldc + col0;
; #pragma unroll
;                 for (int bj = 0; bj < 2; ++bj) {
;                     f32x4 v0, v1;
; #pragma unroll
;                     for (int j = 0; j < 4; ++j) { v0[j] = (float)acc[ai][bj][m][0][j] * rs * sw[bj][0][j] + bv[bj][0][j]; v1[j] = (float)acc[ai][bj][m][1][j] * rs * sw[bj][1][j] + bv[bj][1][j]; }
;                     if (MODE == 1) {
; #pragma unroll
;                         for (int j = 0; j < 4; ++j) { v0[j] = sigm(v0[j]); v1[j] = sigm(v1[j]); } }
;                     u32x4 w; w.x = cvt_pk_bf16(v0[0], v0[1]); w.y = cvt_pk_bf16(v0[2], v0[3]); w.z = cvt_pk_bf16(v1[0], v1[1]); w.w = cvt_pk_bf16(v1[2], v1[3]);
;                     *(u32x4*)(rowp + bj * HALF) = w;
;                 }
	v_mul_f32_e32 v130, v140, v161
	v_mul_f32_e32 v131, v174, v161
	v_mul_f32_e32 v135, v141, v161
	v_mul_f32_e32 v140, v175, v161
	v_mul_f32_e32 v141, v142, v161
	v_mul_f32_e32 v142, v178, v161
	v_mul_f32_e32 v143, v143, v161
	v_mul_f32_e32 v172, v179, v161
	v_mul_f32_e32 v132, v132, v161
	v_mul_f32_e32 v173, v180, v161
	v_mul_f32_e32 v133, v133, v161
	v_fma_f32 v130, v116, v130, 0
	v_fma_f32 v180, v112, v131, 0
	v_fma_f32 v131, v117, v135, 0
	v_mul_f32_e32 v174, v181, v161
	v_mul_f32_e32 v175, v182, v161
	v_mul_f32_e32 v178, v183, v161
	v_mul_f32_e32 v179, v184, v161
	v_mul_f32_e32 v161, v185, v161
	v_fma_f32 v135, v113, v140, 0
	v_fma_f32 v140, v118, v141, 0
	v_fma_f32 v141, v114, v142, 0
	v_fma_f32 v142, v119, v143, 0
	v_fma_f32 v143, v115, v172, 0
	v_fma_f32 v172, v108, v132, 0
	v_fma_f32 v181, v109, v133, 0
	v_cvt_pk_bf16_f32 v130, v130, v131
	v_cvt_pk_bf16_f32 v131, v140, v142
	v_cvt_pk_bf16_f32 v132, v180, v135
	v_cvt_pk_bf16_f32 v133, v141, v143
	v_fma_f32 v173, v104, v173, 0
	v_fma_f32 v174, v105, v174, 0
	v_fma_f32 v175, v110, v175, 0
	v_fma_f32 v178, v106, v178, 0
	v_fma_f32 v179, v111, v179, 0
	v_fma_f32 v161, v107, v161, 0
	global_store_dwordx4 v[136:137], v[130:133], off
	v_cvt_f32_i32_e32 v135, v96
	v_cvt_f32_i32_e32 v25, v25
	v_cvt_pk_bf16_f32 v130, v172, v181
	v_cvt_pk_bf16_f32 v131, v175, v179
	v_cvt_pk_bf16_f32 v132, v173, v174
	v_cvt_pk_bf16_f32 v133, v178, v161
	global_store_dwordx4 v[136:137], v[130:133], off offset:256
	s_nop 1
	v_mov_b32_e32 v130, v190
	v_cvt_f32_i32_e32 v136, v101
	v_cvt_f32_i32_e32 v131, v120
	v_cvt_f32_i32_e32 v132, v121
	v_cvt_f32_i32_e32 v133, v100
	v_cvt_f32_i32_e32 v137, v97
	v_cvt_f32_i32_e32 v138, v102
	v_cvt_f32_i32_e32 v139, v103
	v_or_b32_e32 v100, 32, v160
	v_mad_i64_i32 v[96:97], s[22:23], v134, s42, v[162:163]
	v_ashrrev_i32_e32 v101, 31, v100
	v_lshl_add_u64 v[102:103], v[96:97], 0, v[128:129]
	v_lshl_add_u64 v[120:121], v[100:101], 2, s[2:3]
	v_cvt_f32_i32_e32 v30, v30
	v_cvt_f32_i32_e32 v26, v26
	v_cvt_f32_i32_e32 v31, v31
	v_cvt_f32_i32_e32 v27, v27
	v_cvt_f32_i32_e32 v22, v22
	v_cvt_f32_i32_e32 v18, v18
	v_cvt_f32_i32_e32 v23, v23
	v_cvt_f32_i32_e32 v19, v19
	v_cvt_f32_i32_e32 v12, v12
	v_cvt_f32_i32_e32 v8, v8
	v_cvt_f32_i32_e32 v13, v13
	v_cvt_f32_i32_e32 v9, v9
	v_cvt_f32_i32_e32 v14, v14
	v_cvt_f32_i32_e32 v10, v10
	v_cvt_f32_i32_e32 v15, v15
	v_cvt_f32_i32_e32 v11, v11
	v_cvt_f32_i32_e32 v6, v6
	v_cvt_f32_i32_e32 v2, v2
	v_cvt_f32_i32_e32 v7, v7
	v_cvt_f32_i32_e32 v3, v3
	s_and_b64 vcc, exec, s[0:1]
	s_mov_b32 s43, s12
	s_mov_b32 s20, s14
	s_mov_b64 s[24:25], s[18:19]
	v_mul_f32_e32 v96, v124, v130
	v_mul_f32_e32 v97, v131, v130
	v_mul_f32_e32 v101, v125, v130
	v_mul_f32_e32 v124, v132, v130
	v_mul_f32_e32 v125, v126, v130
	v_mul_f32_e32 v122, v122, v130
	v_mul_f32_e32 v126, v127, v130
	v_mul_f32_e32 v123, v123, v130
	v_mul_f32_e32 v127, v133, v130
	v_mul_f32_e32 v131, v135, v130
	v_mul_f32_e32 v132, v136, v130
	v_mul_f32_e32 v133, v137, v130
	v_mul_f32_e32 v134, v138, v130
	v_mul_f32_e32 v98, v98, v130
	v_mul_f32_e32 v135, v139, v130
	v_mul_f32_e32 v99, v99, v130
	v_fma_f32 v96, v116, v96, 0
	v_fma_f32 v130, v112, v97, 0
	v_fma_f32 v97, v117, v101, 0
	v_fma_f32 v101, v113, v124, 0
	v_fma_f32 v124, v118, v125, 0
	v_fma_f32 v122, v114, v122, 0
	v_fma_f32 v125, v119, v126, 0
	v_fma_f32 v123, v115, v123, 0
	v_fma_f32 v126, v108, v127, 0
	v_fma_f32 v127, v104, v131, 0
	v_fma_f32 v131, v109, v132, 0
	v_fma_f32 v132, v105, v133, 0
	v_fma_f32 v133, v110, v134, 0
	v_fma_f32 v134, v106, v98, 0
	v_fma_f32 v136, v107, v99, 0
	v_cvt_pk_bf16_f32 v96, v96, v97
	v_cvt_pk_bf16_f32 v97, v124, v125
	v_cvt_pk_bf16_f32 v98, v130, v101
	v_cvt_pk_bf16_f32 v99, v122, v123
	v_fma_f32 v135, v111, v135, 0
	global_store_dwordx4 v[102:103], v[96:99], off
	v_cvt_f32_i32_e32 v101, v80
	s_nop 0
	v_cvt_pk_bf16_f32 v96, v126, v131
	v_cvt_pk_bf16_f32 v97, v133, v135
	v_cvt_pk_bf16_f32 v98, v127, v132
	v_cvt_pk_bf16_f32 v99, v134, v136
	global_store_dwordx4 v[102:103], v[96:99], off offset:256
	s_nop 1
	v_mov_b32_e32 v96, v191
	v_cvt_f32_i32_e32 v102, v85
	v_cvt_f32_i32_e32 v97, v88
	v_cvt_f32_i32_e32 v98, v89
	v_cvt_f32_i32_e32 v99, v84
	v_cvt_f32_i32_e32 v103, v81
	v_cvt_f32_i32_e32 v120, v86
	v_cvt_f32_i32_e32 v121, v87
	v_or_b32_e32 v84, 48, v160
	v_mad_i64_i32 v[80:81], s[22:23], v100, s42, v[162:163]
	v_ashrrev_i32_e32 v85, 31, v84
	v_lshl_add_u64 v[86:87], v[80:81], 0, v[128:129]
	v_lshl_add_u64 v[88:89], v[84:85], 2, s[2:3]
	v_mul_f32_e32 v80, v92, v96
	v_mul_f32_e32 v81, v97, v96
	v_mul_f32_e32 v85, v93, v96
	v_mul_f32_e32 v92, v98, v96
	v_mul_f32_e32 v93, v94, v96
	v_mul_f32_e32 v90, v90, v96
	v_mul_f32_e32 v94, v95, v96
	v_mul_f32_e32 v91, v91, v96
	v_mul_f32_e32 v95, v99, v96
	v_mul_f32_e32 v97, v101, v96
	v_mul_f32_e32 v98, v102, v96
	v_mul_f32_e32 v99, v103, v96
	v_mul_f32_e32 v100, v120, v96
	v_mul_f32_e32 v82, v82, v96
	v_mul_f32_e32 v101, v121, v96
	v_mul_f32_e32 v83, v83, v96
	v_fma_f32 v80, v116, v80, 0
	v_fma_f32 v96, v112, v81, 0
	v_fma_f32 v81, v117, v85, 0
	v_fma_f32 v85, v113, v92, 0
	v_fma_f32 v92, v118, v93, 0
	v_fma_f32 v90, v114, v90, 0
	v_fma_f32 v93, v119, v94, 0
	v_fma_f32 v91, v115, v91, 0
	v_fma_f32 v94, v108, v95, 0
	v_fma_f32 v95, v104, v97, 0
	v_fma_f32 v97, v109, v98, 0
	v_fma_f32 v98, v105, v99, 0
	v_fma_f32 v99, v110, v100, 0
	v_fma_f32 v100, v106, v82, 0
	v_fma_f32 v102, v107, v83, 0
	v_cvt_pk_bf16_f32 v80, v80, v81
	v_cvt_pk_bf16_f32 v81, v92, v93
	v_cvt_pk_bf16_f32 v82, v96, v85
	v_cvt_pk_bf16_f32 v83, v90, v91
	v_fma_f32 v101, v111, v101, 0
	global_store_dwordx4 v[86:87], v[80:83], off
	v_cvt_f32_i32_e32 v85, v65
	s_nop 0
	v_cvt_pk_bf16_f32 v80, v94, v97
; __device__ __forceinline__ unsigned cvt_pk_bf16(float lo, float hi) { unsigned r; asm volatile("v_cvt_pk_bf16_f32 %0, %1, %2" : "=v"(r) : "v"(lo), "v"(hi)); return r; }
; __device__ __forceinline__ float ld_agent(const float* p) { return __hip_atomic_load(p, __ATOMIC_RELAXED, __HIP_MEMORY_SCOPE_AGENT); }
; __device__ __forceinline__ float sigm(float x) { return __builtin_amdgcn_rcpf(1.f + __builtin_amdgcn_exp2f(-LOG2E * x)); }
;     __device__ __forceinline__ void operator()(const i32x4 (&acc)[2][2][4][2], const Unit& u, int wr, int wc, int fr_, int fq) const {
;     ...
;         for (int ai = 0; ai < 2; ++ai)
; #pragma unroll
;             for (int m = 0; m < 4; ++m) {
;                 asm volatile("" ::: "memory");
;                 const int r = row0 + ai * HALF + m * 16; const float rs = ld_agent(fr + r);
;                 bf16_t* rowp = O + (size_t)r * ldc + col0;
; #pragma unroll
;                 for (int bj = 0; bj < 2; ++bj) {
;                     f32x4 v0, v1;
; #pragma unroll
;                     for (int j = 0; j < 4; ++j) { v0[j] = (float)acc[ai][bj][m][0][j] * rs * sw[bj][0][j] + bv[bj][0][j]; v1[j] = (float)acc[ai][bj][m][1][j] * rs * sw[bj][1][j] + bv[bj][1][j]; }
;                     if (MODE == 1) {
; #pragma unroll
;                         for (int j = 0; j < 4; ++j) { v0[j] = sigm(v0[j]); v1[j] = sigm(v1[j]); } }
;                     u32x4 w; w.x = cvt_pk_bf16(v0[0], v0[1]); w.y = cvt_pk_bf16(v0[2], v0[3]); w.z = cvt_pk_bf16(v1[0], v1[1]); w.w = cvt_pk_bf16(v1[2], v1[3]);
;                     *(u32x4*)(rowp + bj * HALF) = w;
;                 }
	v_cvt_pk_bf16_f32 v81, v99, v101
	v_cvt_pk_bf16_f32 v82, v95, v98
	v_cvt_pk_bf16_f32 v83, v100, v102
	global_store_dwordx4 v[86:87], v[80:83], off offset:256
	s_nop 1
	v_mov_b32_e32 v80, v192
	v_mul_f32_e32 v73, v73, v80
	v_cvt_f32_i32_e32 v81, v68
	v_cvt_f32_i32_e32 v82, v64
	v_cvt_f32_i32_e32 v83, v69
	v_mad_i64_i32 v[64:65], s[22:23], v84, s42, v[162:163]
	v_lshl_add_u64 v[68:69], v[64:65], 0, v[128:129]
	v_mul_f32_e32 v64, v76, v80
	v_mul_f32_e32 v65, v72, v80
	v_mul_f32_e32 v72, v77, v80
	v_mul_f32_e32 v76, v78, v80
	v_mul_f32_e32 v74, v74, v80
	v_mul_f32_e32 v77, v79, v80
	v_mul_f32_e32 v75, v75, v80
	v_mul_f32_e32 v78, v81, v80
	v_mul_f32_e32 v79, v82, v80
	v_mul_f32_e32 v81, v83, v80
	v_mul_f32_e32 v82, v85, v80
	v_mul_f32_e32 v70, v70, v80
	v_mul_f32_e32 v66, v66, v80
	v_mul_f32_e32 v71, v71, v80
	v_mul_f32_e32 v67, v67, v80
	v_fma_f32 v64, v116, v64, 0
	v_fma_f32 v80, v112, v65, 0
	v_fma_f32 v65, v117, v72, 0
	v_fma_f32 v72, v113, v73, 0
	v_fma_f32 v73, v118, v76, 0
	v_fma_f32 v74, v114, v74, 0
	v_fma_f32 v76, v119, v77, 0
	v_fma_f32 v75, v115, v75, 0
	v_fma_f32 v77, v108, v78, 0
	v_fma_f32 v78, v104, v79, 0
	v_fma_f32 v79, v109, v81, 0
	v_fma_f32 v81, v105, v82, 0
	v_fma_f32 v82, v106, v66, 0
	v_fma_f32 v83, v107, v67, 0
	v_cvt_pk_bf16_f32 v64, v64, v65
	v_cvt_pk_bf16_f32 v65, v73, v76
	v_cvt_pk_bf16_f32 v66, v80, v72
	v_cvt_pk_bf16_f32 v67, v74, v75
	v_fma_f32 v70, v110, v70, 0
	v_fma_f32 v71, v111, v71, 0
	global_store_dwordx4 v[68:69], v[64:67], off
	s_nop 1
	v_cvt_pk_bf16_f32 v64, v77, v79
	v_cvt_pk_bf16_f32 v65, v70, v71
	v_cvt_pk_bf16_f32 v66, v78, v81
	v_cvt_pk_bf16_f32 v67, v82, v83
	global_store_dwordx4 v[68:69], v[64:67], off offset:256
	s_nop 1
	v_mov_b32_e32 v64, v193
	v_cvt_f32_i32_e32 v68, v49
	v_cvt_f32_i32_e32 v65, v52
	v_cvt_f32_i32_e32 v66, v48
	v_cvt_f32_i32_e32 v67, v53
	v_add_u32_e32 v48, 0x80, v160
	v_mad_i64_i32 v[48:49], s[22:23], v48, s42, v[162:163]
	v_lshl_add_u64 v[52:53], v[48:49], 0, v[128:129]
	v_mul_f32_e32 v48, v60, v64
	v_mul_f32_e32 v49, v56, v64
	v_mul_f32_e32 v56, v61, v64
	v_mul_f32_e32 v57, v57, v64
	v_mul_f32_e32 v60, v62, v64
	v_mul_f32_e32 v58, v58, v64
	v_mul_f32_e32 v61, v63, v64
	v_mul_f32_e32 v59, v59, v64
	v_mul_f32_e32 v62, v65, v64
	v_mul_f32_e32 v63, v66, v64
	v_mul_f32_e32 v65, v67, v64
	v_mul_f32_e32 v66, v68, v64
	v_mul_f32_e32 v54, v54, v64
	v_mul_f32_e32 v50, v50, v64
	v_mul_f32_e32 v55, v55, v64
	v_mul_f32_e32 v51, v51, v64
	v_fma_f32 v48, v116, v48, 0
	v_fma_f32 v64, v112, v49, 0
	v_fma_f32 v49, v117, v56, 0
	v_fma_f32 v56, v113, v57, 0
	v_fma_f32 v57, v118, v60, 0
	v_fma_f32 v58, v114, v58, 0
	v_fma_f32 v60, v119, v61, 0
	v_fma_f32 v59, v115, v59, 0
	v_fma_f32 v61, v108, v62, 0
	v_fma_f32 v62, v104, v63, 0
	v_fma_f32 v63, v109, v65, 0
	v_fma_f32 v65, v105, v66, 0
	v_fma_f32 v66, v106, v50, 0
	v_fma_f32 v67, v107, v51, 0
	v_cvt_pk_bf16_f32 v48, v48, v49
	v_cvt_pk_bf16_f32 v49, v57, v60
	v_cvt_pk_bf16_f32 v50, v64, v56
	v_cvt_pk_bf16_f32 v51, v58, v59
	v_fma_f32 v54, v110, v54, 0
	v_fma_f32 v55, v111, v55, 0
	global_store_dwordx4 v[52:53], v[48:51], off
	s_nop 1
	v_cvt_pk_bf16_f32 v48, v61, v63
	v_cvt_pk_bf16_f32 v49, v54, v55
	v_cvt_pk_bf16_f32 v50, v62, v65
	v_cvt_pk_bf16_f32 v51, v66, v67
	global_store_dwordx4 v[52:53], v[48:51], off offset:256
	s_nop 1
	v_mov_b32_e32 v48, v194
	v_cvt_f32_i32_e32 v52, v33
	v_cvt_f32_i32_e32 v49, v36
	v_cvt_f32_i32_e32 v50, v32
	v_cvt_f32_i32_e32 v51, v37
	v_add_u32_e32 v32, 0x90, v160
	v_mad_i64_i32 v[32:33], s[22:23], v32, s42, v[162:163]
	v_lshl_add_u64 v[36:37], v[32:33], 0, v[128:129]
	v_mul_f32_e32 v32, v44, v48
	v_mul_f32_e32 v33, v40, v48
	v_mul_f32_e32 v40, v45, v48
	v_mul_f32_e32 v41, v41, v48
	v_mul_f32_e32 v44, v46, v48
	v_mul_f32_e32 v42, v42, v48
	v_mul_f32_e32 v45, v47, v48
	v_mul_f32_e32 v43, v43, v48
	v_mul_f32_e32 v46, v49, v48
	v_mul_f32_e32 v47, v50, v48
	v_mul_f32_e32 v49, v51, v48
	v_mul_f32_e32 v50, v52, v48
	v_mul_f32_e32 v38, v38, v48
	v_mul_f32_e32 v34, v34, v48
	v_mul_f32_e32 v39, v39, v48
	v_mul_f32_e32 v35, v35, v48
	v_fma_f32 v32, v116, v32, 0
; __device__ __forceinline__ unsigned cvt_pk_bf16(float lo, float hi) { unsigned r; asm volatile("v_cvt_pk_bf16_f32 %0, %1, %2" : "=v"(r) : "v"(lo), "v"(hi)); return r; }
; __device__ __forceinline__ float ld_agent(const float* p) { return __hip_atomic_load(p, __ATOMIC_RELAXED, __HIP_MEMORY_SCOPE_AGENT); }
; __device__ __forceinline__ float sigm(float x) { return __builtin_amdgcn_rcpf(1.f + __builtin_amdgcn_exp2f(-LOG2E * x)); }
;     __device__ __forceinline__ void operator()(const i32x4 (&acc)[2][2][4][2], const Unit& u, int wr, int wc, int fr_, int fq) const {
;     ...
;         for (int ai = 0; ai < 2; ++ai)
; #pragma unroll
;             for (int m = 0; m < 4; ++m) {
;                 asm volatile("" ::: "memory");
;                 const int r = row0 + ai * HALF + m * 16; const float rs = ld_agent(fr + r);
;                 bf16_t* rowp = O + (size_t)r * ldc + col0;
; #pragma unroll
;                 for (int bj = 0; bj < 2; ++bj) {
;                     f32x4 v0, v1;
; #pragma unroll
;                     for (int j = 0; j < 4; ++j) { v0[j] = (float)acc[ai][bj][m][0][j] * rs * sw[bj][0][j] + bv[bj][0][j]; v1[j] = (float)acc[ai][bj][m][1][j] * rs * sw[bj][1][j] + bv[bj][1][j]; }
;                     if (MODE == 1) {
; #pragma unroll
;                         for (int j = 0; j < 4; ++j) { v0[j] = sigm(v0[j]); v1[j] = sigm(v1[j]); } }
;                     u32x4 w; w.x = cvt_pk_bf16(v0[0], v0[1]); w.y = cvt_pk_bf16(v0[2], v0[3]); w.z = cvt_pk_bf16(v1[0], v1[1]); w.w = cvt_pk_bf16(v1[2], v1[3]);
;                     *(u32x4*)(rowp + bj * HALF) = w;
;                 }
; template <class Epi, class Sched>
; __device__ __forceinline__ void gemm_phase(LAS unsigned char* lds, const Gemm g, const Sched& S, const Epi& E) {
;     ...
;         E(acc, cur, wr, wc, fr, fq);
;         if (!has_next) break;
	v_fma_f32 v48, v112, v33, 0
	v_fma_f32 v33, v117, v40, 0
	v_fma_f32 v40, v113, v41, 0
	v_fma_f32 v41, v118, v44, 0
	v_fma_f32 v42, v114, v42, 0
	v_fma_f32 v44, v119, v45, 0
	v_fma_f32 v43, v115, v43, 0
	v_fma_f32 v45, v108, v46, 0
	v_fma_f32 v46, v104, v47, 0
	v_fma_f32 v47, v109, v49, 0
	v_fma_f32 v49, v105, v50, 0
	v_fma_f32 v50, v106, v34, 0
	v_fma_f32 v51, v107, v35, 0
	v_cvt_pk_bf16_f32 v32, v32, v33
	v_cvt_pk_bf16_f32 v33, v41, v44
	v_cvt_pk_bf16_f32 v34, v48, v40
	v_cvt_pk_bf16_f32 v35, v42, v43
	v_fma_f32 v38, v110, v38, 0
	v_fma_f32 v39, v111, v39, 0
	global_store_dwordx4 v[36:37], v[32:35], off
	s_nop 1
	v_cvt_pk_bf16_f32 v32, v45, v47
	v_cvt_pk_bf16_f32 v33, v38, v39
	v_cvt_pk_bf16_f32 v34, v46, v49
	v_cvt_pk_bf16_f32 v35, v50, v51
	global_store_dwordx4 v[36:37], v[32:35], off offset:256
	s_nop 1
	v_mov_b32_e32 v32, v195
	v_cvt_f32_i32_e32 v36, v17
	v_cvt_f32_i32_e32 v33, v20
	v_cvt_f32_i32_e32 v34, v16
	v_cvt_f32_i32_e32 v35, v21
	v_add_u32_e32 v16, 0xa0, v160
	v_mad_i64_i32 v[16:17], s[22:23], v16, s42, v[162:163]
	v_lshl_add_u64 v[20:21], v[16:17], 0, v[128:129]
	s_mov_b64 s[22:23], s[16:17]
	v_mul_f32_e32 v16, v28, v32
	v_mul_f32_e32 v17, v24, v32
	v_mul_f32_e32 v24, v29, v32
	v_mul_f32_e32 v25, v25, v32
	v_mul_f32_e32 v28, v30, v32
	v_mul_f32_e32 v26, v26, v32
	v_mul_f32_e32 v29, v31, v32
	v_mul_f32_e32 v27, v27, v32
	v_mul_f32_e32 v30, v33, v32
	v_mul_f32_e32 v31, v34, v32
	v_mul_f32_e32 v33, v35, v32
	v_mul_f32_e32 v34, v36, v32
	v_mul_f32_e32 v22, v22, v32
	v_mul_f32_e32 v18, v18, v32
	v_mul_f32_e32 v23, v23, v32
	v_mul_f32_e32 v19, v19, v32
	v_fma_f32 v16, v116, v16, 0
	v_fma_f32 v32, v112, v17, 0
	v_fma_f32 v17, v117, v24, 0
	v_fma_f32 v24, v113, v25, 0
	v_fma_f32 v25, v118, v28, 0
	v_fma_f32 v26, v114, v26, 0
	v_fma_f32 v28, v119, v29, 0
	v_fma_f32 v27, v115, v27, 0
	v_fma_f32 v29, v108, v30, 0
	v_fma_f32 v30, v104, v31, 0
	v_fma_f32 v31, v109, v33, 0
	v_fma_f32 v33, v105, v34, 0
	v_fma_f32 v34, v106, v18, 0
	v_fma_f32 v35, v107, v19, 0
	v_cvt_pk_bf16_f32 v16, v16, v17
	v_cvt_pk_bf16_f32 v17, v25, v28
	v_cvt_pk_bf16_f32 v18, v32, v24
	v_cvt_pk_bf16_f32 v19, v26, v27
	v_fma_f32 v22, v110, v22, 0
	v_fma_f32 v23, v111, v23, 0
	global_store_dwordx4 v[20:21], v[16:19], off
	s_nop 1
	v_cvt_pk_bf16_f32 v16, v29, v31
	v_cvt_pk_bf16_f32 v17, v22, v23
	v_cvt_pk_bf16_f32 v18, v30, v33
	v_cvt_pk_bf16_f32 v19, v34, v35
	global_store_dwordx4 v[20:21], v[16:19], off offset:256
	s_nop 1
	v_mov_b32_e32 v16, v196
	v_cvt_f32_i32_e32 v20, v1
	v_cvt_f32_i32_e32 v17, v4
	v_cvt_f32_i32_e32 v18, v0
	v_cvt_f32_i32_e32 v19, v5
	v_add_u32_e32 v0, 0xb0, v160
	v_mad_i64_i32 v[0:1], s[0:1], v0, s42, v[162:163]
	v_lshl_add_u64 v[4:5], v[0:1], 0, v[128:129]
	v_mul_f32_e32 v0, v12, v16
	v_mul_f32_e32 v1, v8, v16
	v_mul_f32_e32 v8, v13, v16
	v_mul_f32_e32 v9, v9, v16
	v_mul_f32_e32 v12, v14, v16
	v_mul_f32_e32 v10, v10, v16
	v_mul_f32_e32 v13, v15, v16
	v_mul_f32_e32 v11, v11, v16
	v_mul_f32_e32 v14, v17, v16
	v_mul_f32_e32 v15, v18, v16
	v_mul_f32_e32 v17, v19, v16
	v_mul_f32_e32 v18, v20, v16
	v_mul_f32_e32 v6, v6, v16
	v_mul_f32_e32 v2, v2, v16
	v_mul_f32_e32 v7, v7, v16
	v_mul_f32_e32 v3, v3, v16
	v_fma_f32 v0, v116, v0, 0
	v_fma_f32 v16, v112, v1, 0
	v_fma_f32 v1, v117, v8, 0
	v_fma_f32 v8, v113, v9, 0
	v_fma_f32 v9, v118, v12, 0
	v_fma_f32 v10, v114, v10, 0
	v_fma_f32 v12, v119, v13, 0
	v_fma_f32 v11, v115, v11, 0
	v_fma_f32 v13, v108, v14, 0
	v_fma_f32 v14, v104, v15, 0
	v_fma_f32 v15, v109, v17, 0
	v_fma_f32 v17, v105, v18, 0
	v_fma_f32 v18, v106, v2, 0
	v_fma_f32 v19, v107, v3, 0
	v_cvt_pk_bf16_f32 v0, v0, v1
	v_cvt_pk_bf16_f32 v1, v9, v12
	v_cvt_pk_bf16_f32 v2, v16, v8
	v_cvt_pk_bf16_f32 v3, v10, v11
	v_fma_f32 v6, v110, v6, 0
	v_fma_f32 v7, v111, v7, 0
	global_store_dwordx4 v[4:5], v[0:3], off
	s_nop 1
	v_cvt_pk_bf16_f32 v0, v13, v15
	v_cvt_pk_bf16_f32 v1, v6, v7
	v_cvt_pk_bf16_f32 v2, v14, v17
	v_cvt_pk_bf16_f32 v3, v18, v19
	global_store_dwordx4 v[4:5], v[0:3], off offset:256
	s_cbranch_vccz .LBB0_383
	s_waitcnt vmcnt(0)
	s_cmpk_gt_u32 s28, 0xff
	s_cbranch_scc1 .LBB0_390
	s_barrier

; #define PG8_STAGE(bufoff, gbase, voff) do { _Pragma("unroll") for (int _i = 0; _i < 2; ++_i) \
;         __builtin_amdgcn_global_load_lds((const unsigned*)((const char*)(gbase) + (voff)[_i]), (LAS unsigned*)(lds + (bufoff) + ldsw + _i * 8192), 16, 0, 0); } while (0)
; #define PG8_LDA(dst, b, h) do { _Pragma("unroll") for (int m = 0; m < 4; ++m) _Pragma("unroll") for (int k = 0; k < 2; ++k) dst[m][k] = *(const LAS bf16x8*)(lds + PG8_SA(b, h) + aoff + m * 2048 + k * 1024); } while (0)
; #define PG8_LDB(dst, b, h) do { _Pragma("unroll") for (int n = 0; n < 2; ++n) _Pragma("unroll") for (int k = 0; k < 2; ++k) dst[n][k] = *(const LAS bf16x8*)(lds + PG8_SB(b, h) + boff + n * 2048 + k * 1024); } while (0)
; #define PG8_MMA(ai, bj, At, Bt) do { __builtin_amdgcn_s_setprio(1); _Pragma("unroll") for (int m = 0; m < 4; ++m) _Pragma("unroll") for (int n = 0; n < 2; ++n) _Pragma("unroll") for (int k = 0; k < 2; ++k) \
;         acc[ai][bj][m][n] = MmaOp<Epi::I8>::run(Bt[n][k], At[m][k], acc[ai][bj][m][n]); __builtin_amdgcn_s_setprio(0); } while (0)
; #define PG8_WAIT_V(n) asm volatile("s_waitcnt vmcnt(" #n ")" ::: "memory")
; #define PG8_WAIT_L(n) asm volatile("s_waitcnt lgkmcnt(" #n ")" ::: "memory")
; #define PG8_BAR __builtin_amdgcn_s_barrier()
; #define PG8_SCHED __builtin_amdgcn_sched_barrier(0)
; template <class Epi, class Sched>
; __device__ __forceinline__ void gemm_phase(LAS unsigned char* lds, const Gemm g, const Sched& S, const Epi& E) {
;     ...
;             PG8_LDB(B0, 0, 0); PG8_SCHED; PG8_LDA(At, 0, 0); PG8_STAGE(PG8_SA(1, 1), a1 + hstepA, voffA);
;             PG8_WAIT_L(8); PG8_BAR; PG8_WAIT_L(0); PG8_MMA(0, 0, At, B0); PG8_BAR; PG8_SCHED;
;             PG8_LDB(B1, 0, 1); PG8_STAGE(PG8_SB(0, 0), b2, voffB);
;             PG8_BAR; PG8_WAIT_L(0); PG8_MMA(0, 1, At, B1); PG8_BAR;
;             PG8_LDA(At, 0, 1); PG8_STAGE(PG8_SA(0, 0), a2, voffA);
;             PG8_BAR; PG8_WAIT_L(0); PG8_MMA(1, 0, At, B0); PG8_BAR; PG8_SCHED;
;             PG8_STAGE(PG8_SB(0, 1), b2 + hstepB, voffB);
;             PG8_WAIT_V(6); PG8_BAR; PG8_MMA(1, 1, At, B1); PG8_BAR;
;             PG8_LDB(B0, 1, 0); PG8_SCHED; PG8_LDA(At, 1, 0); PG8_STAGE(PG8_SA(0, 1), a2 + hstepA, voffA);
;             PG8_WAIT_L(8); PG8_BAR; PG8_WAIT_L(0); PG8_MMA(0, 0, At, B0); PG8_BAR; PG8_SCHED;
.LBB0_635:
	ds_read_b128 v[56:59], v169
	ds_read_b128 v[60:63], v169 offset:1024
	ds_read_b128 v[72:75], v169 offset:2048
	ds_read_b128 v[76:79], v169 offset:3072
	s_add_u32 s30, s28, 0xfff80080
	s_addc_u32 s31, s29, -1
	s_cmp_eq_u32 s59, 12
	s_cselect_b32 s35, s21, s31
	s_cselect_b32 s34, s55, s30
	s_cselect_b32 s31, s19, s58
	s_cselect_b32 s30, s56, s57
	v_lshl_add_u64 v[164:165], s[28:29], 0, v[152:153]
	s_add_i32 m0, s27, 0xc000
	ds_read_b128 v[160:163], v170
	ds_read_b128 v[178:181], v170 offset:1024
	ds_read_b128 v[182:185], v170 offset:2048
	ds_read_b128 v[186:189], v170 offset:3072
	ds_read_b128 v[190:193], v170 offset:4096
	ds_read_b128 v[194:197], v170 offset:5120
	ds_read_b128 v[198:201], v170 offset:6144
	ds_read_b128 v[202:205], v170 offset:7168
	global_load_lds_dwordx4 v[164:165], off
	v_lshl_add_u64 v[164:165], s[28:29], 0, v[154:155]
	s_add_i32 m0, s27, 0xe000
	s_nop 0
	global_load_lds_dwordx4 v[164:165], off
	s_waitcnt lgkmcnt(8)
	s_barrier
	s_waitcnt lgkmcnt(0)
	s_setprio 1
	s_waitcnt lgkmcnt(0)
	v_mfma_i32_16x16x64_i8 v[140:143], v[56:59], v[160:163], v[140:143]
	v_mfma_i32_16x16x64_i8 v[136:139], v[72:75], v[160:163], v[136:139]
	v_mfma_i32_16x16x64_i8 v[124:127], v[56:59], v[182:185], v[124:127]
	v_mfma_i32_16x16x64_i8 v[120:123], v[72:75], v[182:185], v[120:123]
	v_mfma_i32_16x16x64_i8 v[108:111], v[56:59], v[190:193], v[108:111]
	v_mfma_i32_16x16x64_i8 v[104:107], v[72:75], v[190:193], v[104:107]
	v_mfma_i32_16x16x64_i8 v[92:95], v[56:59], v[198:201], v[92:95]
	v_mfma_i32_16x16x64_i8 v[88:91], v[72:75], v[198:201], v[88:91]
	v_mfma_i32_16x16x64_i8 v[140:143], v[60:63], v[178:181], v[140:143]
	v_mfma_i32_16x16x64_i8 v[136:139], v[76:79], v[178:181], v[136:139]
	v_mfma_i32_16x16x64_i8 v[124:127], v[60:63], v[186:189], v[124:127]
	v_mfma_i32_16x16x64_i8 v[120:123], v[76:79], v[186:189], v[120:123]
	v_mfma_i32_16x16x64_i8 v[108:111], v[60:63], v[194:197], v[108:111]
	v_mfma_i32_16x16x64_i8 v[104:107], v[76:79], v[194:197], v[104:107]
	v_mfma_i32_16x16x64_i8 v[92:95], v[60:63], v[202:205], v[92:95]
	v_mfma_i32_16x16x64_i8 v[88:91], v[76:79], v[202:205], v[88:91]
	s_setprio 0
	s_barrier
	s_add_i32 s60, s48, s38
	v_lshl_add_u64 v[164:165], s[30:31], 0, v[148:149]
	s_mov_b32 m0, s60
	ds_read_b128 v[206:209], v171
	ds_read_b128 v[210:213], v171 offset:1024
	ds_read_b128 v[214:217], v171 offset:2048
	ds_read_b128 v[218:221], v171 offset:3072
	global_load_lds_dwordx4 v[164:165], off
	v_lshl_add_u64 v[174:175], s[30:31], 0, v[144:145]
	s_add_i32 m0, s60, 0x2000
	s_nop 0
	global_load_lds_dwordx4 v[174:175], off
	s_barrier
	s_waitcnt lgkmcnt(0)
	s_setprio 1
	s_waitcnt lgkmcnt(0)
	v_mfma_i32_16x16x64_i8 v[132:135], v[206:209], v[160:163], v[132:135]
	v_mfma_i32_16x16x64_i8 v[128:131], v[214:217], v[160:163], v[128:131]
	v_mfma_i32_16x16x64_i8 v[116:119], v[206:209], v[182:185], v[116:119]
	v_mfma_i32_16x16x64_i8 v[112:115], v[214:217], v[182:185], v[112:115]
	v_mfma_i32_16x16x64_i8 v[100:103], v[206:209], v[190:193], v[100:103]
	v_mfma_i32_16x16x64_i8 v[96:99], v[214:217], v[190:193], v[96:99]
	v_mfma_i32_16x16x64_i8 v[84:87], v[206:209], v[198:201], v[84:87]
	v_mfma_i32_16x16x64_i8 v[80:83], v[214:217], v[198:201], v[80:83]
	v_mfma_i32_16x16x64_i8 v[132:135], v[210:213], v[178:181], v[132:135]
	v_mfma_i32_16x16x64_i8 v[128:131], v[218:221], v[178:181], v[128:131]
	v_mfma_i32_16x16x64_i8 v[116:119], v[210:213], v[186:189], v[116:119]
	v_mfma_i32_16x16x64_i8 v[112:115], v[218:221], v[186:189], v[112:115]
	v_mfma_i32_16x16x64_i8 v[100:103], v[210:213], v[194:197], v[100:103]
	v_mfma_i32_16x16x64_i8 v[96:99], v[218:221], v[194:197], v[96:99]
	v_mfma_i32_16x16x64_i8 v[84:87], v[210:213], v[202:205], v[84:87]
	v_mfma_i32_16x16x64_i8 v[80:83], v[218:221], v[202:205], v[80:83]
	s_setprio 0
	s_mov_b32 m0, s27
	v_lshl_add_u64 v[222:223], s[34:35], 0, v[150:151]
	s_barrier
	ds_read_b128 v[160:163], v170 offset:16384
	ds_read_b128 v[178:181], v170 offset:17408
	ds_read_b128 v[182:185], v170 offset:18432
	ds_read_b128 v[186:189], v170 offset:19456
	ds_read_b128 v[190:193], v170 offset:20480
	ds_read_b128 v[194:197], v170 offset:21504
	ds_read_b128 v[198:201], v170 offset:22528
	ds_read_b128 v[202:205], v170 offset:23552
	global_load_lds_dwordx4 v[222:223], off
	v_lshl_add_u64 v[224:225], s[34:35], 0, v[146:147]
	s_mov_b32 m0, s41
	s_nop 0
	global_load_lds_dwordx4 v[224:225], off
	s_barrier
	s_waitcnt lgkmcnt(0)
	s_setprio 1
	s_waitcnt lgkmcnt(0)
	v_mfma_i32_16x16x64_i8 v[68:71], v[56:59], v[160:163], v[68:71]
	v_mfma_i32_16x16x64_i8 v[64:67], v[72:75], v[160:163], v[64:67]
	v_mfma_i32_16x16x64_i8 v[44:47], v[56:59], v[182:185], v[44:47]
	v_mfma_i32_16x16x64_i8 v[40:43], v[72:75], v[182:185], v[40:43]
	v_mfma_i32_16x16x64_i8 v[28:31], v[56:59], v[190:193], v[28:31]
	v_mfma_i32_16x16x64_i8 v[24:27], v[72:75], v[190:193], v[24:27]
	v_mfma_i32_16x16x64_i8 v[12:15], v[56:59], v[198:201], v[12:15]
	v_mfma_i32_16x16x64_i8 v[8:11], v[72:75], v[198:201], v[8:11]
	v_mfma_i32_16x16x64_i8 v[68:71], v[60:63], v[178:181], v[68:71]
	v_mfma_i32_16x16x64_i8 v[64:67], v[76:79], v[178:181], v[64:67]
	v_mfma_i32_16x16x64_i8 v[44:47], v[60:63], v[186:189], v[44:47]
	v_mfma_i32_16x16x64_i8 v[40:43], v[76:79], v[186:189], v[40:43]
	v_mfma_i32_16x16x64_i8 v[28:31], v[60:63], v[194:197], v[28:31]
	v_mfma_i32_16x16x64_i8 v[24:27], v[76:79], v[194:197], v[24:27]
	v_mfma_i32_16x16x64_i8 v[12:15], v[60:63], v[202:205], v[12:15]
	v_mfma_i32_16x16x64_i8 v[8:11], v[76:79], v[202:205], v[8:11]
	s_setprio 0
	s_barrier
; #define PG8_STAGE(bufoff, gbase, voff) do { _Pragma("unroll") for (int _i = 0; _i < 2; ++_i) \
;         __builtin_amdgcn_global_load_lds((const unsigned*)((const char*)(gbase) + (voff)[_i]), (LAS unsigned*)(lds + (bufoff) + ldsw + _i * 8192), 16, 0, 0); } while (0)
; #define PG8_LDA(dst, b, h) do { _Pragma("unroll") for (int m = 0; m < 4; ++m) _Pragma("unroll") for (int k = 0; k < 2; ++k) dst[m][k] = *(const LAS bf16x8*)(lds + PG8_SA(b, h) + aoff + m * 2048 + k * 1024); } while (0)
; #define PG8_LDB(dst, b, h) do { _Pragma("unroll") for (int n = 0; n < 2; ++n) _Pragma("unroll") for (int k = 0; k < 2; ++k) dst[n][k] = *(const LAS bf16x8*)(lds + PG8_SB(b, h) + boff + n * 2048 + k * 1024); } while (0)
; #define PG8_MMA(ai, bj, At, Bt) do { __builtin_amdgcn_s_setprio(1); _Pragma("unroll") for (int m = 0; m < 4; ++m) _Pragma("unroll") for (int n = 0; n < 2; ++n) _Pragma("unroll") for (int k = 0; k < 2; ++k) \
;         acc[ai][bj][m][n] = MmaOp<Epi::I8>::run(Bt[n][k], At[m][k], acc[ai][bj][m][n]); __builtin_amdgcn_s_setprio(0); } while (0)
; #define PG8_WAIT_V(n) asm volatile("s_waitcnt vmcnt(" #n ")" ::: "memory")
; #define PG8_WAIT_L(n) asm volatile("s_waitcnt lgkmcnt(" #n ")" ::: "memory")
; #define PG8_BAR __builtin_amdgcn_s_barrier()
; #define PG8_SCHED __builtin_amdgcn_sched_barrier(0)
; template <class Epi, class Sched>
; __device__ __forceinline__ void gemm_phase(LAS unsigned char* lds, const Gemm g, const Sched& S, const Epi& E) {
;     ...
;             PG8_STAGE(PG8_SB(0, 1), b2 + hstepB, voffB);
;             PG8_WAIT_V(6); PG8_BAR; PG8_MMA(1, 1, At, B1); PG8_BAR;
;             PG8_LDB(B0, 1, 0); PG8_SCHED; PG8_LDA(At, 1, 0); PG8_STAGE(PG8_SA(0, 1), a2 + hstepA, voffA);
;             PG8_WAIT_L(8); PG8_BAR; PG8_WAIT_L(0); PG8_MMA(0, 0, At, B0); PG8_BAR; PG8_SCHED;
;             PG8_LDB(B1, 1, 1); PG8_STAGE(PG8_SB(1, 0), b3, voffB);
;             PG8_BAR; PG8_WAIT_L(0); PG8_MMA(0, 1, At, B1); PG8_BAR;
;             PG8_LDA(At, 1, 1); PG8_STAGE(PG8_SA(1, 0), a3, voffA);
;             PG8_BAR; PG8_WAIT_L(0); PG8_MMA(1, 0, At, B0); PG8_BAR; PG8_SCHED;
;             PG8_STAGE(PG8_SB(1, 1), b3 + hstepB, voffB);
;             PG8_WAIT_V(6); PG8_BAR; PG8_MMA(1, 1, At, B1); PG8_BAR;
	s_add_u32 s60, s30, 0x40000
	s_addc_u32 s61, s31, 0
	s_add_i32 s62, s49, s38
	v_lshl_add_u64 v[56:57], s[60:61], 0, v[148:149]
	s_mov_b32 m0, s62
	s_nop 0
	global_load_lds_dwordx4 v[56:57], off
	v_lshl_add_u64 v[56:57], s[60:61], 0, v[144:145]
	s_add_i32 m0, s62, 0x2000
	s_nop 0
	global_load_lds_dwordx4 v[56:57], off
	s_waitcnt vmcnt(6)
	s_barrier
	s_setprio 1
	v_mfma_i32_16x16x64_i8 v[52:55], v[206:209], v[160:163], v[52:55]
	v_mfma_i32_16x16x64_i8 v[48:51], v[214:217], v[160:163], v[48:51]
	v_mfma_i32_16x16x64_i8 v[36:39], v[206:209], v[182:185], v[36:39]
	v_mfma_i32_16x16x64_i8 v[32:35], v[214:217], v[182:185], v[32:35]
	v_mfma_i32_16x16x64_i8 v[20:23], v[206:209], v[190:193], v[20:23]
	v_mfma_i32_16x16x64_i8 v[16:19], v[214:217], v[190:193], v[16:19]
	v_mfma_i32_16x16x64_i8 v[4:7], v[206:209], v[198:201], v[4:7]
	v_mfma_i32_16x16x64_i8 v[0:3], v[214:217], v[198:201], v[0:3]
	v_mfma_i32_16x16x64_i8 v[52:55], v[210:213], v[178:181], v[52:55]
	v_mfma_i32_16x16x64_i8 v[48:51], v[218:221], v[178:181], v[48:51]
	v_mfma_i32_16x16x64_i8 v[36:39], v[210:213], v[186:189], v[36:39]
	v_mfma_i32_16x16x64_i8 v[32:35], v[218:221], v[186:189], v[32:35]
	v_mfma_i32_16x16x64_i8 v[20:23], v[210:213], v[194:197], v[20:23]
	v_mfma_i32_16x16x64_i8 v[16:19], v[218:221], v[194:197], v[16:19]
	v_mfma_i32_16x16x64_i8 v[4:7], v[210:213], v[202:205], v[4:7]
	v_mfma_i32_16x16x64_i8 v[0:3], v[218:221], v[202:205], v[0:3]
	s_setprio 0
	s_add_i32 s60, 0, 0x18000
	v_add_u32_e32 v76, s60, v167
	s_barrier
	ds_read_b128 v[56:59], v76
	ds_read_b128 v[60:63], v76 offset:1024
	ds_read_b128 v[72:75], v76 offset:2048
	ds_read_b128 v[76:79], v76 offset:3072
	s_add_u32 s34, s34, 0x80000
	s_addc_u32 s35, s35, 0
	s_mov_b32 m0, s42
	v_lshl_add_u64 v[206:207], s[34:35], 0, v[150:151]
	ds_read_b128 v[160:163], v170 offset:32768
	ds_read_b128 v[178:181], v170 offset:33792
	ds_read_b128 v[182:185], v170 offset:34816
	ds_read_b128 v[186:189], v170 offset:35840
	ds_read_b128 v[190:193], v170 offset:36864
	ds_read_b128 v[194:197], v170 offset:37888
	ds_read_b128 v[198:201], v170 offset:38912
	ds_read_b128 v[202:205], v170 offset:39936
	global_load_lds_dwordx4 v[206:207], off
	v_lshl_add_u64 v[206:207], s[34:35], 0, v[146:147]
	s_mov_b32 m0, s43
	s_nop 0
	global_load_lds_dwordx4 v[206:207], off
	s_waitcnt lgkmcnt(8)
	s_barrier
	s_waitcnt lgkmcnt(0)
	s_setprio 1
	s_waitcnt lgkmcnt(0)
	v_mfma_i32_16x16x64_i8 v[140:143], v[56:59], v[160:163], v[140:143]
	v_mfma_i32_16x16x64_i8 v[136:139], v[72:75], v[160:163], v[136:139]
	v_mfma_i32_16x16x64_i8 v[124:127], v[56:59], v[182:185], v[124:127]
	v_mfma_i32_16x16x64_i8 v[120:123], v[72:75], v[182:185], v[120:123]
	v_mfma_i32_16x16x64_i8 v[108:111], v[56:59], v[190:193], v[108:111]
	v_mfma_i32_16x16x64_i8 v[104:107], v[72:75], v[190:193], v[104:107]
	v_mfma_i32_16x16x64_i8 v[92:95], v[56:59], v[198:201], v[92:95]
	v_mfma_i32_16x16x64_i8 v[88:91], v[72:75], v[198:201], v[88:91]
	v_mfma_i32_16x16x64_i8 v[140:143], v[60:63], v[178:181], v[140:143]
	v_mfma_i32_16x16x64_i8 v[136:139], v[76:79], v[178:181], v[136:139]
	v_mfma_i32_16x16x64_i8 v[124:127], v[60:63], v[186:189], v[124:127]
	v_mfma_i32_16x16x64_i8 v[120:123], v[76:79], v[186:189], v[120:123]
	v_mfma_i32_16x16x64_i8 v[108:111], v[60:63], v[194:197], v[108:111]
	v_mfma_i32_16x16x64_i8 v[104:107], v[76:79], v[194:197], v[104:107]
	v_mfma_i32_16x16x64_i8 v[92:95], v[60:63], v[202:205], v[92:95]
	v_mfma_i32_16x16x64_i8 v[88:91], v[76:79], v[202:205], v[88:91]
	s_setprio 0
	s_barrier
	s_add_i32 s34, 0, 0x1c000
	s_add_i32 s35, s60, s38
	v_add_u32_e32 v173, s34, v167
	v_lshl_add_u64 v[164:165], v[164:165], 0, s[8:9]
	s_mov_b32 m0, s35
	ds_read_b128 v[206:209], v173
	ds_read_b128 v[210:213], v173 offset:1024
	ds_read_b128 v[214:217], v173 offset:2048
	ds_read_b128 v[218:221], v173 offset:3072
	global_load_lds_dwordx4 v[164:165], off
	v_lshl_add_u64 v[164:165], v[174:175], 0, s[8:9]
	s_add_i32 m0, s35, 0x2000
	s_nop 0
	global_load_lds_dwordx4 v[164:165], off
	s_barrier
	s_waitcnt lgkmcnt(0)
	s_setprio 1
	s_waitcnt lgkmcnt(0)
	v_mfma_i32_16x16x64_i8 v[132:135], v[206:209], v[160:163], v[132:135]
	v_mfma_i32_16x16x64_i8 v[128:131], v[214:217], v[160:163], v[128:131]
	v_mfma_i32_16x16x64_i8 v[116:119], v[206:209], v[182:185], v[116:119]
	v_mfma_i32_16x16x64_i8 v[112:115], v[214:217], v[182:185], v[112:115]
	v_mfma_i32_16x16x64_i8 v[100:103], v[206:209], v[190:193], v[100:103]
	v_mfma_i32_16x16x64_i8 v[96:99], v[214:217], v[190:193], v[96:99]
	v_mfma_i32_16x16x64_i8 v[84:87], v[206:209], v[198:201], v[84:87]
	v_mfma_i32_16x16x64_i8 v[80:83], v[214:217], v[198:201], v[80:83]
	v_mfma_i32_16x16x64_i8 v[132:135], v[210:213], v[178:181], v[132:135]
	v_mfma_i32_16x16x64_i8 v[128:131], v[218:221], v[178:181], v[128:131]
	v_mfma_i32_16x16x64_i8 v[116:119], v[210:213], v[186:189], v[116:119]
	v_mfma_i32_16x16x64_i8 v[112:115], v[218:221], v[186:189], v[112:115]
	v_mfma_i32_16x16x64_i8 v[100:103], v[210:213], v[194:197], v[100:103]
	v_mfma_i32_16x16x64_i8 v[96:99], v[218:221], v[194:197], v[96:99]
	v_mfma_i32_16x16x64_i8 v[84:87], v[210:213], v[202:205], v[84:87]
	v_mfma_i32_16x16x64_i8 v[80:83], v[218:221], v[202:205], v[80:83]
	s_setprio 0
	s_mov_b32 m0, s45
	v_lshl_add_u64 v[164:165], v[222:223], 0, s[8:9]
	s_barrier
	ds_read_b128 v[160:163], v170 offset:49152
	ds_read_b128 v[178:181], v170 offset:50176
	ds_read_b128 v[182:185], v170 offset:51200
	ds_read_b128 v[186:189], v170 offset:52224
	ds_read_b128 v[190:193], v170 offset:53248
	ds_read_b128 v[194:197], v170 offset:54272
	ds_read_b128 v[198:201], v170 offset:55296
	ds_read_b128 v[202:205], v170 offset:56320
	global_load_lds_dwordx4 v[164:165], off
	v_lshl_add_u64 v[164:165], v[224:225], 0, s[8:9]
	s_mov_b32 m0, s46
	s_nop 0
	global_load_lds_dwordx4 v[164:165], off
	s_barrier
; __device__ __forceinline__ float rs_of(const float* ssq, int r) { return __builtin_amdgcn_rsqf(ld_agent(ssq + r) * (1.f / 2048.f) + EPS); }
; #define PG8_STAGE(bufoff, gbase, voff) do { _Pragma("unroll") for (int _i = 0; _i < 2; ++_i) \
;         __builtin_amdgcn_global_load_lds((const unsigned*)((const char*)(gbase) + (voff)[_i]), (LAS unsigned*)(lds + (bufoff) + ldsw + _i * 8192), 16, 0, 0); } while (0)
; #define PG8_MMA(ai, bj, At, Bt) do { __builtin_amdgcn_s_setprio(1); _Pragma("unroll") for (int m = 0; m < 4; ++m) _Pragma("unroll") for (int n = 0; n < 2; ++n) _Pragma("unroll") for (int k = 0; k < 2; ++k) \
;         acc[ai][bj][m][n] = MmaOp<Epi::I8>::run(Bt[n][k], At[m][k], acc[ai][bj][m][n]); __builtin_amdgcn_s_setprio(0); } while (0)
; #define PG8_WAIT_V(n) asm volatile("s_waitcnt vmcnt(" #n ")" ::: "memory")
; #define PG8_WAIT_L(n) asm volatile("s_waitcnt lgkmcnt(" #n ")" ::: "memory")
; #define PG8_BAR __builtin_amdgcn_s_barrier()
; #define PG8_SCHED __builtin_amdgcn_sched_barrier(0)
;     __device__ __forceinline__ void operator()(const i32x4 (&acc)[2][2][4][2], const Unit& u, int wr, int wc, int fr, int fq) const {
;         const int row0 = u.pm * BM + wr * 64 + fr, col0 = u.pn * BM + wc * 32 + 8 * fq;
;         f32x4 bv[2][2];
; #pragma unroll
;         for (int bj = 0; bj < 2; ++bj)
; #pragma unroll
;             for (int n = 0; n < 2; ++n) bv[bj][n] = *(const f32x4*)(bias + col0 + bj * HALF + 4 * n);
; #pragma unroll
;         for (int ai = 0; ai < 2; ++ai)
; #pragma unroll
;             for (int m = 0; m < 4; ++m) {
;                 const int r = row0 + ai * HALF + m * 16; const float rs = rs_of(ssq, r);
;                 bf16_t* rowp = O + (size_t)r * ldc + col0;
; #pragma unroll
;                 for (int bj = 0; bj < 2; ++bj) {
;                     const f32x4 s0 = *(const f32x4*)(swp + col0 + bj * HALF), s1 = *(const f32x4*)(swp + col0 + bj * HALF + 4);
; template <class Epi, class Sched>
; __device__ __forceinline__ void gemm_phase(LAS unsigned char* lds, const Gemm g, const Sched& S, const Epi& E) {
;     ...
;             PG8_BAR; PG8_WAIT_L(0); PG8_MMA(1, 0, At, B0); PG8_BAR; PG8_SCHED;
;             PG8_STAGE(PG8_SB(1, 1), b3 + hstepB, voffB);
;             PG8_WAIT_V(6); PG8_BAR; PG8_MMA(1, 1, At, B1); PG8_BAR;
	s_waitcnt lgkmcnt(0)
	s_setprio 1
	s_waitcnt lgkmcnt(0)
	v_mfma_i32_16x16x64_i8 v[68:71], v[56:59], v[160:163], v[68:71]
	v_mfma_i32_16x16x64_i8 v[64:67], v[72:75], v[160:163], v[64:67]
	v_mfma_i32_16x16x64_i8 v[44:47], v[56:59], v[182:185], v[44:47]
	v_mfma_i32_16x16x64_i8 v[40:43], v[72:75], v[182:185], v[40:43]
	v_mfma_i32_16x16x64_i8 v[28:31], v[56:59], v[190:193], v[28:31]
	v_mfma_i32_16x16x64_i8 v[24:27], v[72:75], v[190:193], v[24:27]
	v_mfma_i32_16x16x64_i8 v[12:15], v[56:59], v[198:201], v[12:15]
	v_mfma_i32_16x16x64_i8 v[8:11], v[72:75], v[198:201], v[8:11]
	v_mfma_i32_16x16x64_i8 v[68:71], v[60:63], v[178:181], v[68:71]
	v_mfma_i32_16x16x64_i8 v[64:67], v[76:79], v[178:181], v[64:67]
	v_mfma_i32_16x16x64_i8 v[44:47], v[60:63], v[186:189], v[44:47]
	v_mfma_i32_16x16x64_i8 v[40:43], v[76:79], v[186:189], v[40:43]
	v_mfma_i32_16x16x64_i8 v[28:31], v[60:63], v[194:197], v[28:31]
	v_mfma_i32_16x16x64_i8 v[24:27], v[76:79], v[194:197], v[24:27]
	v_mfma_i32_16x16x64_i8 v[12:15], v[60:63], v[202:205], v[12:15]
	v_mfma_i32_16x16x64_i8 v[8:11], v[76:79], v[202:205], v[8:11]
	s_setprio 0
	s_barrier
	s_add_u32 s30, s30, 0x40080
	s_addc_u32 s31, s31, 0
	s_add_i32 s34, s34, s38
	v_lshl_add_u64 v[56:57], s[30:31], 0, v[148:149]
	s_mov_b32 m0, s34
	s_nop 0
	global_load_lds_dwordx4 v[56:57], off
	v_lshl_add_u64 v[56:57], s[30:31], 0, v[144:145]
	s_add_i32 m0, s34, 0x2000
	s_nop 0
	global_load_lds_dwordx4 v[56:57], off
	s_waitcnt vmcnt(6)
	s_barrier
	s_setprio 1
	v_mfma_i32_16x16x64_i8 v[52:55], v[206:209], v[160:163], v[52:55]
	v_mfma_i32_16x16x64_i8 v[48:51], v[214:217], v[160:163], v[48:51]
	v_mfma_i32_16x16x64_i8 v[36:39], v[206:209], v[182:185], v[36:39]
	v_mfma_i32_16x16x64_i8 v[32:35], v[214:217], v[182:185], v[32:35]
	v_mfma_i32_16x16x64_i8 v[20:23], v[206:209], v[190:193], v[20:23]
	v_mfma_i32_16x16x64_i8 v[16:19], v[214:217], v[190:193], v[16:19]
	v_mfma_i32_16x16x64_i8 v[4:7], v[206:209], v[198:201], v[4:7]
	v_mfma_i32_16x16x64_i8 v[0:3], v[214:217], v[198:201], v[0:3]
	v_mfma_i32_16x16x64_i8 v[52:55], v[210:213], v[178:181], v[52:55]
	v_mfma_i32_16x16x64_i8 v[48:51], v[218:221], v[178:181], v[48:51]
	v_mfma_i32_16x16x64_i8 v[36:39], v[210:213], v[186:189], v[36:39]
	v_mfma_i32_16x16x64_i8 v[32:35], v[218:221], v[186:189], v[32:35]
	v_mfma_i32_16x16x64_i8 v[20:23], v[210:213], v[194:197], v[20:23]
	v_mfma_i32_16x16x64_i8 v[16:19], v[218:221], v[194:197], v[16:19]
	v_mfma_i32_16x16x64_i8 v[4:7], v[210:213], v[202:205], v[4:7]
	v_mfma_i32_16x16x64_i8 v[0:3], v[218:221], v[202:205], v[0:3]
	s_setprio 0
	s_add_i32 s59, s59, 2
	s_add_u32 s28, s28, 0x100
	s_addc_u32 s29, s29, 0
	s_add_u32 s57, s57, 0x100
	s_addc_u32 s58, s58, 0
	s_cmp_gt_u32 s59, 13
	s_barrier
	s_cbranch_scc0 .LBB0_635
	v_lshl_or_b32 v174, s54, 8, v168
	v_ashrrev_i32_e32 v175, 31, v174
	v_readlane_b32 s76, v239, 2
	v_lshl_add_u32 v164, s26, 8, v166
	v_lshlrev_b64 v[160:161], 2, v[174:175]
	v_readlane_b32 s90, v239, 16
	v_readlane_b32 s91, v239, 17
	v_ashrrev_i32_e32 v165, 31, v164
	v_lshl_add_u64 v[162:163], v[164:165], 2, s[4:5]
	v_lshl_add_u64 v[60:61], s[90:91], 0, v[160:161]
	global_load_dwordx4 v[72:75], v[60:61], off offset:16
	global_load_dwordx4 v[76:79], v[60:61], off
	global_load_dwordx4 v[56:59], v[60:61], off offset:528
	s_nop 0
	global_load_dwordx4 v[60:63], v[60:61], off offset:512
	v_lshl_add_u64 v[160:161], s[6:7], 0, v[160:161]
	global_load_dword v173, v[162:163], off sc1
	global_load_dword v206, v[162:163], off offset:64 sc1
	global_load_dword v207, v[162:163], off offset:128 sc1
	global_load_dword v208, v[162:163], off offset:192 sc1
	global_load_dword v209, v[162:163], off offset:512 sc1
	global_load_dword v210, v[162:163], off offset:576 sc1
	global_load_dword v211, v[162:163], off offset:640 sc1
	global_load_dword v212, v[162:163], off offset:704 sc1
	global_load_dwordx4 v[178:181], v[160:161], off
	global_load_dwordx4 v[182:185], v[160:161], off offset:16
	global_load_dwordx4 v[190:193], v[160:161], off
	global_load_dwordx4 v[194:197], v[160:161], off offset:16
	global_load_dwordx4 v[198:201], v[160:161], off offset:512
	global_load_dwordx4 v[202:205], v[160:161], off offset:528
	v_cvt_f32_i32_e32 v141, v141
	v_cvt_f32_i32_e32 v140, v140
	v_cvt_f32_i32_e32 v143, v143
	v_cvt_f32_i32_e32 v142, v142
	v_cvt_f32_i32_e32 v187, v137
	v_cvt_f32_i32_e32 v186, v136
	v_lshlrev_b64 v[136:137], 13, v[164:165]
	v_cvt_f32_i32_e32 v189, v139
	v_cvt_f32_i32_e32 v188, v138
	v_lshlrev_b64 v[138:139], 1, v[174:175]
	v_readlane_b32 s28, v239, 46
	v_readlane_b32 s29, v239, 47
	v_cvt_f32_i32_e32 v133, v133
	v_cvt_f32_i32_e32 v132, v132
	v_lshl_add_u64 v[136:137], s[28:29], 0, v[136:137]
	v_lshl_add_u64 v[136:137], v[136:137], 0, v[138:139]
	v_cvt_f32_i32_e32 v135, v135
	v_cvt_f32_i32_e32 v134, v134
	v_cvt_f32_i32_e32 v129, v129
	v_cvt_f32_i32_e32 v128, v128
	v_cvt_f32_i32_e32 v131, v131
	v_cvt_f32_i32_e32 v130, v130
	v_cvt_f32_i32_e32 v127, v127
	v_cvt_f32_i32_e32 v126, v126
	v_cvt_f32_i32_e32 v125, v125
	v_cvt_f32_i32_e32 v124, v124
	v_cvt_f32_i32_e32 v121, v121
	v_cvt_f32_i32_e32 v120, v120
	v_cvt_f32_i32_e32 v123, v123
	v_cvt_f32_i32_e32 v122, v122
	v_cvt_f32_i32_e32 v117, v117
	v_cvt_f32_i32_e32 v116, v116
	v_cvt_f32_i32_e32 v119, v119
	v_cvt_f32_i32_e32 v118, v118
	v_cvt_f32_i32_e32 v113, v113
	v_cvt_f32_i32_e32 v112, v112
	v_cvt_f32_i32_e32 v115, v115
	v_cvt_f32_i32_e32 v114, v114
	v_cvt_f32_i32_e32 v111, v111
	v_cvt_f32_i32_e32 v110, v110
	v_cvt_f32_i32_e32 v109, v109
	v_cvt_f32_i32_e32 v108, v108
	v_cvt_f32_i32_e32 v105, v105
	v_cvt_f32_i32_e32 v104, v104
	v_cvt_f32_i32_e32 v107, v107
	v_cvt_f32_i32_e32 v106, v106
	v_cvt_f32_i32_e32 v101, v101
	v_cvt_f32_i32_e32 v100, v100
	v_cvt_f32_i32_e32 v103, v103
	v_cvt_f32_i32_e32 v102, v102
	v_cvt_f32_i32_e32 v97, v97
	v_cvt_f32_i32_e32 v96, v96
	v_cvt_f32_i32_e32 v99, v99
	v_cvt_f32_i32_e32 v98, v98
	v_cvt_f32_i32_e32 v95, v95
	v_cvt_f32_i32_e32 v94, v94
	v_cvt_f32_i32_e32 v93, v93
	v_cvt_f32_i32_e32 v92, v92
	v_cvt_f32_i32_e32 v89, v89
	v_cvt_f32_i32_e32 v88, v88
	v_cvt_f32_i32_e32 v91, v91
	v_cvt_f32_i32_e32 v90, v90
	v_cvt_f32_i32_e32 v85, v85
	v_cvt_f32_i32_e32 v84, v84
	v_cvt_f32_i32_e32 v87, v87
	v_cvt_f32_i32_e32 v86, v86
	v_cvt_f32_i32_e32 v81, v81
	v_cvt_f32_i32_e32 v83, v83
	v_cvt_f32_i32_e32 v82, v82
	v_cvt_f32_i32_e32 v80, v80
	v_cvt_f32_i32_e32 v71, v71
	v_cvt_f32_i32_e32 v70, v70
	v_cvt_f32_i32_e32 v69, v69
	v_cvt_f32_i32_e32 v68, v68
	v_cvt_f32_i32_e32 v65, v65
	v_cvt_f32_i32_e32 v64, v64
	v_cvt_f32_i32_e32 v67, v67
	v_cvt_f32_i32_e32 v66, v66
	s_waitcnt vmcnt(0)
; __device__ __forceinline__ unsigned cvt_pk_bf16(float lo, float hi) { unsigned r; asm volatile("v_cvt_pk_bf16_f32 %0, %1, %2" : "=v"(r) : "v"(lo), "v"(hi)); return r; }
; __device__ __forceinline__ float ld_agent(const float* p) { return __hip_atomic_load(p, __ATOMIC_RELAXED, __HIP_MEMORY_SCOPE_AGENT); }
; __device__ __forceinline__ float rs_of(const float* ssq, int r) { return __builtin_amdgcn_rsqf(ld_agent(ssq + r) * (1.f / 2048.f) + EPS); }
; __device__ __forceinline__ float sigm(float x) { return __builtin_amdgcn_rcpf(1.f + __builtin_amdgcn_exp2f(-LOG2E * x)); }
;     __device__ __forceinline__ void operator()(const i32x4 (&acc)[2][2][4][2], const Unit& u, int wr, int wc, int fr, int fq) const {
;     ...
;         for (int ai = 0; ai < 2; ++ai)
; #pragma unroll
;             for (int m = 0; m < 4; ++m) {
;                 const int r = row0 + ai * HALF + m * 16; const float rs = rs_of(ssq, r);
;                 bf16_t* rowp = O + (size_t)r * ldc + col0;
; #pragma unroll
;                 for (int bj = 0; bj < 2; ++bj) {
;                     const f32x4 s0 = *(const f32x4*)(swp + col0 + bj * HALF), s1 = *(const f32x4*)(swp + col0 + bj * HALF + 4);
;                     f32x4 v0 = __builtin_convertvector(acc[ai][bj][m][0], f32x4) * s0 * rs + bv[bj][0], v1 = __builtin_convertvector(acc[ai][bj][m][1], f32x4) * s1 * rs + bv[bj][1];
; #pragma unroll
;                     for (int j = 0; j < 4; ++j) { v0[j] = sigm(v0[j]); v1[j] = sigm(v1[j]); }
;                     u32x4 w; w.x = cvt_pk_bf16(v0[0], v0[1]); w.y = cvt_pk_bf16(v0[2], v0[3]); w.z = cvt_pk_bf16(v1[0], v1[1]); w.w = cvt_pk_bf16(v1[2], v1[3]);
;                     *(u32x4*)(rowp + bj * HALF) = w;
;                 }
;             }
	v_fmamk_f32 v165, v173, 0x3a000000, v172
	v_rsq_f32_e32 v174, v165
	v_pk_mul_f32 v[142:143], v[180:181], v[142:143]
	v_pk_mul_f32 v[140:141], v[178:179], v[140:141]
	v_pk_mul_f32 v[178:179], v[184:185], v[188:189]
	v_pk_mul_f32 v[180:181], v[182:183], v[186:187]
	v_pk_fma_f32 v[142:143], v[142:143], v[174:175], v[78:79] op_sel_hi:[1,0,1]
	v_pk_fma_f32 v[140:141], v[140:141], v[174:175], v[76:77] op_sel_hi:[1,0,1]
	v_pk_fma_f32 v[178:179], v[178:179], v[174:175], v[74:75] op_sel_hi:[1,0,1]
	v_pk_fma_f32 v[180:181], v[180:181], v[174:175], v[72:73] op_sel_hi:[1,0,1]
	v_mul_f32_e32 v140, 0xbfb8aa3b, v140
	v_mul_f32_e32 v141, 0xbfb8aa3b, v141
	v_mul_f32_e32 v142, 0xbfb8aa3b, v142
	v_mul_f32_e32 v143, 0xbfb8aa3b, v143
	v_mul_f32_e32 v165, 0xbfb8aa3b, v180
	v_mul_f32_e32 v173, 0xbfb8aa3b, v181
	v_mul_f32_e32 v175, 0xbfb8aa3b, v178
	v_mul_f32_e32 v178, 0xbfb8aa3b, v179
	v_exp_f32_e32 v140, v140
	v_exp_f32_e32 v141, v141
	v_exp_f32_e32 v142, v142
	v_exp_f32_e32 v143, v143
	v_exp_f32_e32 v165, v165
	v_exp_f32_e32 v173, v173
	v_exp_f32_e32 v175, v175
	v_exp_f32_e32 v178, v178
	v_add_f32_e32 v140, 1.0, v140
	v_add_f32_e32 v141, 1.0, v141
	v_add_f32_e32 v142, 1.0, v142
	v_add_f32_e32 v143, 1.0, v143
	v_add_f32_e32 v165, 1.0, v165
	v_add_f32_e32 v173, 1.0, v173
	v_add_f32_e32 v175, 1.0, v175
	v_add_f32_e32 v178, 1.0, v178
	v_rcp_f32_e32 v140, v140
	v_rcp_f32_e32 v141, v141
	v_rcp_f32_e32 v142, v142
	v_rcp_f32_e32 v143, v143
	v_rcp_f32_e32 v165, v165
	v_rcp_f32_e32 v173, v173
	v_rcp_f32_e32 v175, v175
	v_rcp_f32_e32 v178, v178
	v_cvt_pk_bf16_f32 v140, v140, v141
	v_cvt_pk_bf16_f32 v141, v142, v143
	v_cvt_pk_bf16_f32 v142, v165, v173
	v_cvt_pk_bf16_f32 v143, v175, v178
	global_store_dwordx4 v[136:137], v[140:143], off
	s_nop 1
	v_mov_b64_e32 v[140:141], v[198:199]
	v_mov_b64_e32 v[142:143], v[200:201]
	s_nop 0
	v_mov_b64_e32 v[178:179], v[202:203]
	v_mov_b64_e32 v[180:181], v[204:205]
	v_or_b32_e32 v182, 16, v164
	v_ashrrev_i32_e32 v183, 31, v182
	v_lshl_add_u64 v[184:185], v[182:183], 2, s[4:5]
	v_cvt_f32_i32_e32 v53, v53
	v_cvt_f32_i32_e32 v52, v52
	v_cvt_f32_i32_e32 v55, v55
	v_cvt_f32_i32_e32 v54, v54
	v_cvt_f32_i32_e32 v49, v49
	v_cvt_f32_i32_e32 v48, v48
	v_cvt_f32_i32_e32 v51, v51
	v_cvt_f32_i32_e32 v50, v50
	v_cvt_f32_i32_e32 v47, v47
	v_cvt_f32_i32_e32 v46, v46
	v_cvt_f32_i32_e32 v45, v45
	v_cvt_f32_i32_e32 v44, v44
	v_cvt_f32_i32_e32 v41, v41
	v_cvt_f32_i32_e32 v40, v40
	v_cvt_f32_i32_e32 v43, v43
	v_cvt_f32_i32_e32 v42, v42
	v_cvt_f32_i32_e32 v37, v37
	v_cvt_f32_i32_e32 v36, v36
	v_cvt_f32_i32_e32 v39, v39
	v_cvt_f32_i32_e32 v38, v38
	v_cvt_f32_i32_e32 v33, v33
	v_cvt_f32_i32_e32 v32, v32
	v_cvt_f32_i32_e32 v35, v35
	v_cvt_f32_i32_e32 v34, v34
	v_cvt_f32_i32_e32 v31, v31
	v_cvt_f32_i32_e32 v30, v30
	v_cvt_f32_i32_e32 v29, v29
	v_cvt_f32_i32_e32 v28, v28
	v_cvt_f32_i32_e32 v25, v25
	v_cvt_f32_i32_e32 v24, v24
	v_cvt_f32_i32_e32 v27, v27
	v_cvt_f32_i32_e32 v26, v26
	v_cvt_f32_i32_e32 v21, v21
	v_cvt_f32_i32_e32 v20, v20
	v_cvt_f32_i32_e32 v23, v23
	v_cvt_f32_i32_e32 v22, v22
	v_cvt_f32_i32_e32 v17, v17
	v_cvt_f32_i32_e32 v16, v16
	v_cvt_f32_i32_e32 v19, v19
	v_cvt_f32_i32_e32 v18, v18
	v_cvt_f32_i32_e32 v15, v15
	v_cvt_f32_i32_e32 v14, v14
	v_cvt_f32_i32_e32 v13, v13
	v_cvt_f32_i32_e32 v12, v12
	v_cvt_f32_i32_e32 v9, v9
	v_cvt_f32_i32_e32 v8, v8
	v_cvt_f32_i32_e32 v11, v11
	v_cvt_f32_i32_e32 v10, v10
	v_cvt_f32_i32_e32 v5, v5
	v_cvt_f32_i32_e32 v4, v4
	v_cvt_f32_i32_e32 v7, v7
	v_cvt_f32_i32_e32 v6, v6
	v_cvt_f32_i32_e32 v1, v1
	v_cvt_f32_i32_e32 v0, v0
	v_cvt_f32_i32_e32 v3, v3
	v_cvt_f32_i32_e32 v2, v2
	s_mov_b32 s54, s18
	s_mov_b32 s26, s20
	s_mov_b64 s[30:31], s[24:25]
	v_readlane_b32 s61, v239, 50
	v_readlane_b32 s77, v239, 3
	v_readlane_b32 s78, v239, 4
	v_readlane_b32 s79, v239, 5
	v_readlane_b32 s80, v239, 6
	v_readlane_b32 s81, v239, 7
	v_readlane_b32 s82, v239, 8
	v_readlane_b32 s83, v239, 9
	v_readlane_b32 s84, v239, 10
	v_readlane_b32 s85, v239, 11
	v_readlane_b32 s86, v239, 12
	v_readlane_b32 s87, v239, 13
	v_readlane_b32 s88, v239, 14
	v_readlane_b32 s89, v239, 15
	v_pk_mul_f32 v[134:135], v[142:143], v[134:135]
	v_pk_mul_f32 v[132:133], v[140:141], v[132:133]
	v_pk_mul_f32 v[130:131], v[180:181], v[130:131]
	v_pk_mul_f32 v[128:129], v[178:179], v[128:129]
	v_pk_fma_f32 v[134:135], v[174:175], v[134:135], v[62:63] op_sel_hi:[0,1,1]
	v_pk_fma_f32 v[132:133], v[174:175], v[132:133], v[60:61] op_sel_hi:[0,1,1]
	v_pk_fma_f32 v[130:131], v[174:175], v[130:131], v[58:59] op_sel_hi:[0,1,1]
	v_pk_fma_f32 v[128:129], v[174:175], v[128:129], v[56:57] op_sel_hi:[0,1,1]
	v_mul_f32_e32 v128, 0xbfb8aa3b, v128
	v_mul_f32_e32 v133, 0xbfb8aa3b, v133
	v_mul_f32_e32 v129, 0xbfb8aa3b, v129
	v_mul_f32_e32 v134, 0xbfb8aa3b, v134
	v_mul_f32_e32 v131, 0xbfb8aa3b, v131
	v_mul_f32_e32 v132, 0xbfb8aa3b, v132
	v_mul_f32_e32 v130, 0xbfb8aa3b, v130
	v_mul_f32_e32 v135, 0xbfb8aa3b, v135
	v_exp_f32_e32 v128, v128
	v_exp_f32_e32 v133, v133
	v_exp_f32_e32 v129, v129
	v_exp_f32_e32 v134, v134
	v_exp_f32_e32 v131, v131
	v_exp_f32_e32 v132, v132
	v_exp_f32_e32 v130, v130
	v_exp_f32_e32 v135, v135
	v_add_f32_e32 v128, 1.0, v128
	v_add_f32_e32 v133, 1.0, v133
	v_add_f32_e32 v129, 1.0, v129
	v_add_f32_e32 v134, 1.0, v134
	v_add_f32_e32 v131, 1.0, v131
	v_add_f32_e32 v132, 1.0, v132
	v_add_f32_e32 v130, 1.0, v130
	v_add_f32_e32 v135, 1.0, v135
	v_rcp_f32_e32 v140, v128
	v_rcp_f32_e32 v128, v133
	v_rcp_f32_e32 v133, v129
	v_rcp_f32_e32 v129, v134
	v_rcp_f32_e32 v131, v131
	v_rcp_f32_e32 v132, v132
	v_rcp_f32_e32 v134, v135
	v_rcp_f32_e32 v135, v130
	v_cvt_pk_bf16_f32 v128, v132, v128
	v_cvt_pk_bf16_f32 v129, v129, v134
	v_cvt_pk_bf16_f32 v130, v140, v133
; __device__ __forceinline__ unsigned cvt_pk_bf16(float lo, float hi) { unsigned r; asm volatile("v_cvt_pk_bf16_f32 %0, %1, %2" : "=v"(r) : "v"(lo), "v"(hi)); return r; }
; __device__ __forceinline__ float ld_agent(const float* p) { return __hip_atomic_load(p, __ATOMIC_RELAXED, __HIP_MEMORY_SCOPE_AGENT); }
; __device__ __forceinline__ float rs_of(const float* ssq, int r) { return __builtin_amdgcn_rsqf(ld_agent(ssq + r) * (1.f / 2048.f) + EPS); }
; __device__ __forceinline__ float sigm(float x) { return __builtin_amdgcn_rcpf(1.f + __builtin_amdgcn_exp2f(-LOG2E * x)); }
;     __device__ __forceinline__ void operator()(const i32x4 (&acc)[2][2][4][2], const Unit& u, int wr, int wc, int fr, int fq) const {
;     ...
;         for (int ai = 0; ai < 2; ++ai)
; #pragma unroll
;             for (int m = 0; m < 4; ++m) {
;                 const int r = row0 + ai * HALF + m * 16; const float rs = rs_of(ssq, r);
;                 bf16_t* rowp = O + (size_t)r * ldc + col0;
; #pragma unroll
;                 for (int bj = 0; bj < 2; ++bj) {
;                     const f32x4 s0 = *(const f32x4*)(swp + col0 + bj * HALF), s1 = *(const f32x4*)(swp + col0 + bj * HALF + 4);
;                     f32x4 v0 = __builtin_convertvector(acc[ai][bj][m][0], f32x4) * s0 * rs + bv[bj][0], v1 = __builtin_convertvector(acc[ai][bj][m][1], f32x4) * s1 * rs + bv[bj][1];
; #pragma unroll
;                     for (int j = 0; j < 4; ++j) { v0[j] = sigm(v0[j]); v1[j] = sigm(v1[j]); }
;                     u32x4 w; w.x = cvt_pk_bf16(v0[0], v0[1]); w.y = cvt_pk_bf16(v0[2], v0[3]); w.z = cvt_pk_bf16(v1[0], v1[1]); w.w = cvt_pk_bf16(v1[2], v1[3]);
;                     *(u32x4*)(rowp + bj * HALF) = w;
;                 }
;             }
	v_cvt_pk_bf16_f32 v131, v135, v131
	global_store_dwordx4 v[136:137], v[128:131], off offset:256
	s_nop 1
	v_mov_b32_e32 v142, v206
	s_nop 0
	v_mov_b64_e32 v[128:129], v[190:191]
	v_mov_b64_e32 v[130:131], v[192:193]
	v_mov_b64_e32 v[132:133], v[194:195]
	v_mov_b64_e32 v[134:135], v[196:197]
	v_lshlrev_b64 v[140:141], 13, v[182:183]
	v_lshl_add_u64 v[140:141], s[28:29], 0, v[140:141]
	v_lshl_add_u64 v[140:141], v[140:141], 0, v[138:139]
	v_fmamk_f32 v142, v142, 0x3a000000, v172
	v_pk_mul_f32 v[126:127], v[130:131], v[126:127]
	v_rsq_f32_e32 v130, v142
	v_pk_mul_f32 v[124:125], v[128:129], v[124:125]
	v_pk_mul_f32 v[122:123], v[134:135], v[122:123]
	v_pk_mul_f32 v[120:121], v[132:133], v[120:121]
	v_pk_fma_f32 v[126:127], v[126:127], v[130:131], v[78:79] op_sel_hi:[1,0,1]
	v_pk_fma_f32 v[124:125], v[124:125], v[130:131], v[76:77] op_sel_hi:[1,0,1]
	v_pk_fma_f32 v[122:123], v[122:123], v[130:131], v[74:75] op_sel_hi:[1,0,1]
	v_pk_fma_f32 v[120:121], v[120:121], v[130:131], v[72:73] op_sel_hi:[1,0,1]
	v_mul_f32_e32 v125, 0xbfb8aa3b, v125
	v_mul_f32_e32 v120, 0xbfb8aa3b, v120
	v_mul_f32_e32 v121, 0xbfb8aa3b, v121
	v_mul_f32_e32 v126, 0xbfb8aa3b, v126
	v_mul_f32_e32 v123, 0xbfb8aa3b, v123
	v_mul_f32_e32 v124, 0xbfb8aa3b, v124
	v_mul_f32_e32 v122, 0xbfb8aa3b, v122
	v_mul_f32_e32 v127, 0xbfb8aa3b, v127
	v_exp_f32_e32 v120, v120
	v_exp_f32_e32 v125, v125
	v_exp_f32_e32 v121, v121
	v_exp_f32_e32 v126, v126
	v_exp_f32_e32 v123, v123
	v_exp_f32_e32 v124, v124
	v_exp_f32_e32 v122, v122
	v_exp_f32_e32 v127, v127
	v_add_f32_e32 v120, 1.0, v120
	v_add_f32_e32 v125, 1.0, v125
	v_add_f32_e32 v121, 1.0, v121
	v_add_f32_e32 v126, 1.0, v126
	v_add_f32_e32 v123, 1.0, v123
	v_add_f32_e32 v124, 1.0, v124
	v_add_f32_e32 v122, 1.0, v122
	v_add_f32_e32 v127, 1.0, v127
	v_rcp_f32_e32 v128, v120
	v_rcp_f32_e32 v120, v125
	v_rcp_f32_e32 v125, v121
	v_rcp_f32_e32 v121, v126
	v_rcp_f32_e32 v123, v123
	v_rcp_f32_e32 v124, v124
	v_rcp_f32_e32 v126, v127
	v_rcp_f32_e32 v127, v122
	v_cvt_pk_bf16_f32 v120, v124, v120
	v_cvt_pk_bf16_f32 v121, v121, v126
	v_cvt_pk_bf16_f32 v122, v128, v125
	v_cvt_pk_bf16_f32 v123, v127, v123
	global_store_dwordx4 v[140:141], v[120:123], off
	s_nop 1
	v_mov_b64_e32 v[120:121], v[198:199]
	v_mov_b64_e32 v[122:123], v[200:201]
	s_nop 0
	v_mov_b64_e32 v[124:125], v[202:203]
	v_mov_b64_e32 v[126:127], v[204:205]
	v_or_b32_e32 v128, 32, v164
	v_ashrrev_i32_e32 v129, 31, v128
	v_lshl_add_u64 v[132:133], v[128:129], 2, s[4:5]
	v_pk_mul_f32 v[118:119], v[122:123], v[118:119]
	v_pk_mul_f32 v[116:117], v[120:121], v[116:117]
	v_pk_mul_f32 v[114:115], v[126:127], v[114:115]
	v_pk_mul_f32 v[112:113], v[124:125], v[112:113]
	v_pk_fma_f32 v[118:119], v[130:131], v[118:119], v[62:63] op_sel_hi:[0,1,1]
	v_pk_fma_f32 v[116:117], v[130:131], v[116:117], v[60:61] op_sel_hi:[0,1,1]
	v_pk_fma_f32 v[114:115], v[130:131], v[114:115], v[58:59] op_sel_hi:[0,1,1]
	v_pk_fma_f32 v[112:113], v[130:131], v[112:113], v[56:57] op_sel_hi:[0,1,1]
	v_mul_f32_e32 v112, 0xbfb8aa3b, v112
	v_mul_f32_e32 v117, 0xbfb8aa3b, v117
	v_mul_f32_e32 v113, 0xbfb8aa3b, v113
	v_mul_f32_e32 v118, 0xbfb8aa3b, v118
	v_mul_f32_e32 v115, 0xbfb8aa3b, v115
	v_mul_f32_e32 v116, 0xbfb8aa3b, v116
	v_mul_f32_e32 v114, 0xbfb8aa3b, v114
	v_mul_f32_e32 v119, 0xbfb8aa3b, v119
	v_exp_f32_e32 v112, v112
	v_exp_f32_e32 v117, v117
	v_exp_f32_e32 v113, v113
	v_exp_f32_e32 v118, v118
	v_exp_f32_e32 v115, v115
	v_exp_f32_e32 v116, v116
	v_exp_f32_e32 v114, v114
	v_exp_f32_e32 v119, v119
	v_add_f32_e32 v112, 1.0, v112
	v_add_f32_e32 v117, 1.0, v117
	v_add_f32_e32 v113, 1.0, v113
	v_add_f32_e32 v118, 1.0, v118
	v_add_f32_e32 v115, 1.0, v115
	v_add_f32_e32 v116, 1.0, v116
	v_add_f32_e32 v114, 1.0, v114
	v_add_f32_e32 v119, 1.0, v119
	v_rcp_f32_e32 v120, v112
	v_rcp_f32_e32 v112, v117
	v_rcp_f32_e32 v117, v113
	v_rcp_f32_e32 v113, v118
	v_rcp_f32_e32 v115, v115
	v_rcp_f32_e32 v116, v116
	v_rcp_f32_e32 v118, v119
	v_rcp_f32_e32 v119, v114
	v_cvt_pk_bf16_f32 v112, v116, v112
	v_cvt_pk_bf16_f32 v113, v113, v118
	v_cvt_pk_bf16_f32 v114, v120, v117
	v_cvt_pk_bf16_f32 v115, v119, v115
	global_store_dwordx4 v[140:141], v[112:115], off offset:256
	s_nop 1
	v_mov_b32_e32 v122, v207
	s_nop 0
	v_mov_b64_e32 v[112:113], v[190:191]
	v_mov_b64_e32 v[114:115], v[192:193]
	v_mov_b64_e32 v[116:117], v[194:195]
	v_mov_b64_e32 v[118:119], v[196:197]
	v_lshlrev_b64 v[120:121], 13, v[128:129]
	v_lshl_add_u64 v[120:121], s[28:29], 0, v[120:121]
	v_lshl_add_u64 v[120:121], v[120:121], 0, v[138:139]
	v_fmamk_f32 v122, v122, 0x3a000000, v172
	v_pk_mul_f32 v[110:111], v[114:115], v[110:111]
	v_rsq_f32_e32 v114, v122
	v_pk_mul_f32 v[108:109], v[112:113], v[108:109]
	v_pk_mul_f32 v[106:107], v[118:119], v[106:107]
	v_pk_mul_f32 v[104:105], v[116:117], v[104:105]
	v_pk_fma_f32 v[110:111], v[110:111], v[114:115], v[78:79] op_sel_hi:[1,0,1]
	v_pk_fma_f32 v[108:109], v[108:109], v[114:115], v[76:77] op_sel_hi:[1,0,1]
	v_pk_fma_f32 v[106:107], v[106:107], v[114:115], v[74:75] op_sel_hi:[1,0,1]
	v_pk_fma_f32 v[104:105], v[104:105], v[114:115], v[72:73] op_sel_hi:[1,0,1]
	v_mul_f32_e32 v109, 0xbfb8aa3b, v109
	v_mul_f32_e32 v104, 0xbfb8aa3b, v104
	v_mul_f32_e32 v105, 0xbfb8aa3b, v105
	v_mul_f32_e32 v110, 0xbfb8aa3b, v110
	v_mul_f32_e32 v107, 0xbfb8aa3b, v107
	v_mul_f32_e32 v108, 0xbfb8aa3b, v108
	v_mul_f32_e32 v106, 0xbfb8aa3b, v106
	v_mul_f32_e32 v111, 0xbfb8aa3b, v111
	v_exp_f32_e32 v104, v104
	v_exp_f32_e32 v109, v109
	v_exp_f32_e32 v105, v105
	v_exp_f32_e32 v110, v110
	v_exp_f32_e32 v107, v107
	v_exp_f32_e32 v108, v108
	v_exp_f32_e32 v106, v106
	v_exp_f32_e32 v111, v111
	v_add_f32_e32 v104, 1.0, v104
	v_add_f32_e32 v109, 1.0, v109
; __device__ __forceinline__ unsigned cvt_pk_bf16(float lo, float hi) { unsigned r; asm volatile("v_cvt_pk_bf16_f32 %0, %1, %2" : "=v"(r) : "v"(lo), "v"(hi)); return r; }
; __device__ __forceinline__ float ld_agent(const float* p) { return __hip_atomic_load(p, __ATOMIC_RELAXED, __HIP_MEMORY_SCOPE_AGENT); }
; __device__ __forceinline__ float rs_of(const float* ssq, int r) { return __builtin_amdgcn_rsqf(ld_agent(ssq + r) * (1.f / 2048.f) + EPS); }
; __device__ __forceinline__ float sigm(float x) { return __builtin_amdgcn_rcpf(1.f + __builtin_amdgcn_exp2f(-LOG2E * x)); }
;     __device__ __forceinline__ void operator()(const i32x4 (&acc)[2][2][4][2], const Unit& u, int wr, int wc, int fr, int fq) const {
;     ...
;         for (int ai = 0; ai < 2; ++ai)
; #pragma unroll
;             for (int m = 0; m < 4; ++m) {
;                 const int r = row0 + ai * HALF + m * 16; const float rs = rs_of(ssq, r);
;                 bf16_t* rowp = O + (size_t)r * ldc + col0;
; #pragma unroll
;                 for (int bj = 0; bj < 2; ++bj) {
;                     const f32x4 s0 = *(const f32x4*)(swp + col0 + bj * HALF), s1 = *(const f32x4*)(swp + col0 + bj * HALF + 4);
;                     f32x4 v0 = __builtin_convertvector(acc[ai][bj][m][0], f32x4) * s0 * rs + bv[bj][0], v1 = __builtin_convertvector(acc[ai][bj][m][1], f32x4) * s1 * rs + bv[bj][1];
; #pragma unroll
;                     for (int j = 0; j < 4; ++j) { v0[j] = sigm(v0[j]); v1[j] = sigm(v1[j]); }
;                     u32x4 w; w.x = cvt_pk_bf16(v0[0], v0[1]); w.y = cvt_pk_bf16(v0[2], v0[3]); w.z = cvt_pk_bf16(v1[0], v1[1]); w.w = cvt_pk_bf16(v1[2], v1[3]);
;                     *(u32x4*)(rowp + bj * HALF) = w;
;                 }
;             }
	v_add_f32_e32 v105, 1.0, v105
	v_add_f32_e32 v110, 1.0, v110
	v_add_f32_e32 v107, 1.0, v107
	v_add_f32_e32 v108, 1.0, v108
	v_add_f32_e32 v106, 1.0, v106
	v_add_f32_e32 v111, 1.0, v111
	v_rcp_f32_e32 v112, v104
	v_rcp_f32_e32 v104, v109
	v_rcp_f32_e32 v109, v105
	v_rcp_f32_e32 v105, v110
	v_rcp_f32_e32 v107, v107
	v_rcp_f32_e32 v108, v108
	v_rcp_f32_e32 v110, v111
	v_rcp_f32_e32 v111, v106
	v_cvt_pk_bf16_f32 v104, v108, v104
	v_cvt_pk_bf16_f32 v105, v105, v110
	v_cvt_pk_bf16_f32 v106, v112, v109
	v_cvt_pk_bf16_f32 v107, v111, v107
	global_store_dwordx4 v[120:121], v[104:107], off
	s_nop 1
	v_mov_b64_e32 v[104:105], v[198:199]
	v_mov_b64_e32 v[106:107], v[200:201]
	s_nop 0
	v_mov_b64_e32 v[108:109], v[202:203]
	v_mov_b64_e32 v[110:111], v[204:205]
	v_or_b32_e32 v112, 48, v164
	v_ashrrev_i32_e32 v113, 31, v112
	v_lshl_add_u64 v[116:117], v[112:113], 2, s[4:5]
	v_pk_mul_f32 v[102:103], v[106:107], v[102:103]
	v_pk_mul_f32 v[100:101], v[104:105], v[100:101]
	v_pk_mul_f32 v[98:99], v[110:111], v[98:99]
	v_pk_mul_f32 v[96:97], v[108:109], v[96:97]
	v_pk_fma_f32 v[102:103], v[114:115], v[102:103], v[62:63] op_sel_hi:[0,1,1]
	v_pk_fma_f32 v[100:101], v[114:115], v[100:101], v[60:61] op_sel_hi:[0,1,1]
	v_pk_fma_f32 v[98:99], v[114:115], v[98:99], v[58:59] op_sel_hi:[0,1,1]
	v_pk_fma_f32 v[96:97], v[114:115], v[96:97], v[56:57] op_sel_hi:[0,1,1]
	v_mul_f32_e32 v96, 0xbfb8aa3b, v96
	v_mul_f32_e32 v101, 0xbfb8aa3b, v101
	v_mul_f32_e32 v97, 0xbfb8aa3b, v97
	v_mul_f32_e32 v102, 0xbfb8aa3b, v102
	v_mul_f32_e32 v99, 0xbfb8aa3b, v99
	v_mul_f32_e32 v100, 0xbfb8aa3b, v100
	v_mul_f32_e32 v98, 0xbfb8aa3b, v98
	v_mul_f32_e32 v103, 0xbfb8aa3b, v103
	v_exp_f32_e32 v96, v96
	v_exp_f32_e32 v101, v101
	v_exp_f32_e32 v97, v97
	v_exp_f32_e32 v102, v102
	v_exp_f32_e32 v99, v99
	v_exp_f32_e32 v100, v100
	v_exp_f32_e32 v98, v98
	v_exp_f32_e32 v103, v103
	v_add_f32_e32 v96, 1.0, v96
	v_add_f32_e32 v101, 1.0, v101
	v_add_f32_e32 v97, 1.0, v97
	v_add_f32_e32 v102, 1.0, v102
	v_add_f32_e32 v99, 1.0, v99
	v_add_f32_e32 v100, 1.0, v100
	v_add_f32_e32 v98, 1.0, v98
	v_add_f32_e32 v103, 1.0, v103
	v_rcp_f32_e32 v104, v96
	v_rcp_f32_e32 v96, v101
	v_rcp_f32_e32 v101, v97
	v_rcp_f32_e32 v97, v102
	v_rcp_f32_e32 v99, v99
	v_rcp_f32_e32 v100, v100
	v_rcp_f32_e32 v102, v103
	v_rcp_f32_e32 v103, v98
	v_cvt_pk_bf16_f32 v96, v100, v96
	v_cvt_pk_bf16_f32 v97, v97, v102
	v_cvt_pk_bf16_f32 v98, v104, v101
	v_cvt_pk_bf16_f32 v99, v103, v99
	global_store_dwordx4 v[120:121], v[96:99], off offset:256
	s_nop 1
	v_mov_b32_e32 v106, v208
	s_nop 0
	v_mov_b64_e32 v[96:97], v[190:191]
	v_mov_b64_e32 v[98:99], v[192:193]
	v_mov_b64_e32 v[100:101], v[194:195]
	v_mov_b64_e32 v[102:103], v[196:197]
	v_lshlrev_b64 v[104:105], 13, v[112:113]
	v_lshl_add_u64 v[104:105], s[28:29], 0, v[104:105]
	v_lshl_add_u64 v[104:105], v[104:105], 0, v[138:139]
	s_mov_b64 s[28:29], s[22:23]
	v_fmamk_f32 v106, v106, 0x3a000000, v172
	v_pk_mul_f32 v[94:95], v[98:99], v[94:95]
	v_rsq_f32_e32 v98, v106
	v_pk_mul_f32 v[92:93], v[96:97], v[92:93]
	v_pk_mul_f32 v[90:91], v[102:103], v[90:91]
	v_pk_mul_f32 v[88:89], v[100:101], v[88:89]
	v_pk_fma_f32 v[94:95], v[94:95], v[98:99], v[78:79] op_sel_hi:[1,0,1]
	v_pk_fma_f32 v[92:93], v[92:93], v[98:99], v[76:77] op_sel_hi:[1,0,1]
	v_pk_fma_f32 v[90:91], v[90:91], v[98:99], v[74:75] op_sel_hi:[1,0,1]
	v_pk_fma_f32 v[88:89], v[88:89], v[98:99], v[72:73] op_sel_hi:[1,0,1]
	v_mul_f32_e32 v93, 0xbfb8aa3b, v93
	v_mul_f32_e32 v88, 0xbfb8aa3b, v88
	v_mul_f32_e32 v89, 0xbfb8aa3b, v89
	v_mul_f32_e32 v94, 0xbfb8aa3b, v94
	v_mul_f32_e32 v91, 0xbfb8aa3b, v91
	v_mul_f32_e32 v92, 0xbfb8aa3b, v92
	v_mul_f32_e32 v90, 0xbfb8aa3b, v90
	v_mul_f32_e32 v95, 0xbfb8aa3b, v95
	v_exp_f32_e32 v88, v88
	v_exp_f32_e32 v93, v93
	v_exp_f32_e32 v89, v89
	v_exp_f32_e32 v94, v94
	v_exp_f32_e32 v91, v91
	v_exp_f32_e32 v92, v92
	v_exp_f32_e32 v90, v90
	v_exp_f32_e32 v95, v95
	v_add_f32_e32 v88, 1.0, v88
	v_add_f32_e32 v93, 1.0, v93
	v_add_f32_e32 v89, 1.0, v89
	v_add_f32_e32 v94, 1.0, v94
	v_add_f32_e32 v91, 1.0, v91
	v_add_f32_e32 v92, 1.0, v92
	v_add_f32_e32 v90, 1.0, v90
	v_add_f32_e32 v95, 1.0, v95
	v_rcp_f32_e32 v96, v88
	v_rcp_f32_e32 v88, v93
	v_rcp_f32_e32 v93, v89
	v_rcp_f32_e32 v89, v94
	v_rcp_f32_e32 v91, v91
	v_rcp_f32_e32 v92, v92
	v_rcp_f32_e32 v94, v95
	v_rcp_f32_e32 v95, v90
	v_cvt_pk_bf16_f32 v88, v92, v88
	v_cvt_pk_bf16_f32 v89, v89, v94
	v_cvt_pk_bf16_f32 v90, v96, v93
	v_cvt_pk_bf16_f32 v91, v95, v91
	global_store_dwordx4 v[104:105], v[88:91], off
	s_nop 1
	v_mov_b64_e32 v[88:89], v[198:199]
	v_mov_b64_e32 v[90:91], v[200:201]
	s_nop 0
	v_mov_b64_e32 v[92:93], v[202:203]
	v_mov_b64_e32 v[94:95], v[204:205]
	v_pk_mul_f32 v[86:87], v[90:91], v[86:87]
	v_pk_mul_f32 v[84:85], v[88:89], v[84:85]
	v_pk_mul_f32 v[82:83], v[94:95], v[82:83]
	v_pk_mul_f32 v[80:81], v[92:93], v[80:81]
	v_pk_fma_f32 v[86:87], v[98:99], v[86:87], v[62:63] op_sel_hi:[0,1,1]
	v_pk_fma_f32 v[84:85], v[98:99], v[84:85], v[60:61] op_sel_hi:[0,1,1]
	v_pk_fma_f32 v[82:83], v[98:99], v[82:83], v[58:59] op_sel_hi:[0,1,1]
	v_pk_fma_f32 v[80:81], v[98:99], v[80:81], v[56:57] op_sel_hi:[0,1,1]
	v_mul_f32_e32 v80, 0xbfb8aa3b, v80
	v_mul_f32_e32 v85, 0xbfb8aa3b, v85
	v_mul_f32_e32 v81, 0xbfb8aa3b, v81
	v_mul_f32_e32 v86, 0xbfb8aa3b, v86
	v_mul_f32_e32 v83, 0xbfb8aa3b, v83
	v_mul_f32_e32 v84, 0xbfb8aa3b, v84
	v_mul_f32_e32 v82, 0xbfb8aa3b, v82
	v_mul_f32_e32 v87, 0xbfb8aa3b, v87
	v_exp_f32_e32 v80, v80
	v_exp_f32_e32 v85, v85
	v_exp_f32_e32 v81, v81
	v_exp_f32_e32 v86, v86
	v_exp_f32_e32 v83, v83
	v_exp_f32_e32 v84, v84
	v_exp_f32_e32 v82, v82
	v_exp_f32_e32 v87, v87
	v_add_f32_e32 v80, 1.0, v80
	v_add_f32_e32 v85, 1.0, v85
; __device__ __forceinline__ unsigned cvt_pk_bf16(float lo, float hi) { unsigned r; asm volatile("v_cvt_pk_bf16_f32 %0, %1, %2" : "=v"(r) : "v"(lo), "v"(hi)); return r; }
; __device__ __forceinline__ float ld_agent(const float* p) { return __hip_atomic_load(p, __ATOMIC_RELAXED, __HIP_MEMORY_SCOPE_AGENT); }
; __device__ __forceinline__ float rs_of(const float* ssq, int r) { return __builtin_amdgcn_rsqf(ld_agent(ssq + r) * (1.f / 2048.f) + EPS); }
; __device__ __forceinline__ float sigm(float x) { return __builtin_amdgcn_rcpf(1.f + __builtin_amdgcn_exp2f(-LOG2E * x)); }
;     __device__ __forceinline__ void operator()(const i32x4 (&acc)[2][2][4][2], const Unit& u, int wr, int wc, int fr, int fq) const {
;     ...
;         for (int ai = 0; ai < 2; ++ai)
; #pragma unroll
;             for (int m = 0; m < 4; ++m) {
;                 const int r = row0 + ai * HALF + m * 16; const float rs = rs_of(ssq, r);
;                 bf16_t* rowp = O + (size_t)r * ldc + col0;
; #pragma unroll
;                 for (int bj = 0; bj < 2; ++bj) {
;                     const f32x4 s0 = *(const f32x4*)(swp + col0 + bj * HALF), s1 = *(const f32x4*)(swp + col0 + bj * HALF + 4);
;                     f32x4 v0 = __builtin_convertvector(acc[ai][bj][m][0], f32x4) * s0 * rs + bv[bj][0], v1 = __builtin_convertvector(acc[ai][bj][m][1], f32x4) * s1 * rs + bv[bj][1];
; #pragma unroll
;                     for (int j = 0; j < 4; ++j) { v0[j] = sigm(v0[j]); v1[j] = sigm(v1[j]); }
;                     u32x4 w; w.x = cvt_pk_bf16(v0[0], v0[1]); w.y = cvt_pk_bf16(v0[2], v0[3]); w.z = cvt_pk_bf16(v1[0], v1[1]); w.w = cvt_pk_bf16(v1[2], v1[3]);
;                     *(u32x4*)(rowp + bj * HALF) = w;
;                 }
;             }
	v_add_f32_e32 v81, 1.0, v81
	v_add_f32_e32 v86, 1.0, v86
	v_add_f32_e32 v83, 1.0, v83
	v_add_f32_e32 v84, 1.0, v84
	v_add_f32_e32 v82, 1.0, v82
	v_add_f32_e32 v87, 1.0, v87
	v_rcp_f32_e32 v88, v80
	v_rcp_f32_e32 v80, v85
	v_rcp_f32_e32 v85, v81
	v_rcp_f32_e32 v81, v86
	v_rcp_f32_e32 v83, v83
	v_rcp_f32_e32 v84, v84
	v_rcp_f32_e32 v86, v87
	v_rcp_f32_e32 v87, v82
	v_cvt_pk_bf16_f32 v80, v84, v80
	v_cvt_pk_bf16_f32 v81, v81, v86
	v_cvt_pk_bf16_f32 v82, v88, v85
	v_cvt_pk_bf16_f32 v83, v87, v83
	global_store_dwordx4 v[104:105], v[80:83], off offset:256
	s_nop 1
	v_mov_b32_e32 v90, v209
	s_nop 0
	v_mov_b64_e32 v[80:81], v[190:191]
	v_mov_b64_e32 v[82:83], v[192:193]
	v_mov_b64_e32 v[84:85], v[194:195]
	v_mov_b64_e32 v[86:87], v[196:197]
	v_add_co_u32_e32 v88, vcc, s50, v136
	v_fmamk_f32 v90, v90, 0x3a000000, v172
	v_pk_mul_f32 v[70:71], v[82:83], v[70:71]
	v_rsq_f32_e32 v82, v90
	v_pk_mul_f32 v[68:69], v[80:81], v[68:69]
	v_pk_mul_f32 v[66:67], v[86:87], v[66:67]
	v_pk_mul_f32 v[64:65], v[84:85], v[64:65]
	v_pk_fma_f32 v[70:71], v[70:71], v[82:83], v[78:79] op_sel_hi:[1,0,1]
	v_pk_fma_f32 v[68:69], v[68:69], v[82:83], v[76:77] op_sel_hi:[1,0,1]
	v_pk_fma_f32 v[66:67], v[66:67], v[82:83], v[74:75] op_sel_hi:[1,0,1]
	v_pk_fma_f32 v[64:65], v[64:65], v[82:83], v[72:73] op_sel_hi:[1,0,1]
	v_mul_f32_e32 v69, 0xbfb8aa3b, v69
	v_mul_f32_e32 v64, 0xbfb8aa3b, v64
	v_mul_f32_e32 v65, 0xbfb8aa3b, v65
	v_mul_f32_e32 v70, 0xbfb8aa3b, v70
	v_mul_f32_e32 v67, 0xbfb8aa3b, v67
	v_mul_f32_e32 v68, 0xbfb8aa3b, v68
	v_mul_f32_e32 v66, 0xbfb8aa3b, v66
	v_mul_f32_e32 v71, 0xbfb8aa3b, v71
	v_exp_f32_e32 v64, v64
	v_exp_f32_e32 v69, v69
	v_exp_f32_e32 v65, v65
	v_exp_f32_e32 v70, v70
	v_exp_f32_e32 v67, v67
	v_exp_f32_e32 v68, v68
	v_exp_f32_e32 v66, v66
	v_exp_f32_e32 v71, v71
	v_add_f32_e32 v64, 1.0, v64
	v_add_f32_e32 v69, 1.0, v69
	v_add_f32_e32 v65, 1.0, v65
	v_add_f32_e32 v70, 1.0, v70
	v_add_f32_e32 v67, 1.0, v67
	v_addc_co_u32_e32 v89, vcc, 0, v137, vcc
	v_add_f32_e32 v68, 1.0, v68
	v_add_f32_e32 v66, 1.0, v66
	v_add_f32_e32 v71, 1.0, v71
	v_rcp_f32_e32 v80, v64
	v_rcp_f32_e32 v64, v69
	v_rcp_f32_e32 v69, v65
	v_rcp_f32_e32 v65, v70
	v_rcp_f32_e32 v67, v67
	v_rcp_f32_e32 v68, v68
	v_rcp_f32_e32 v70, v71
	v_rcp_f32_e32 v71, v66
	v_cvt_pk_bf16_f32 v64, v68, v64
	v_cvt_pk_bf16_f32 v65, v65, v70
	v_cvt_pk_bf16_f32 v66, v80, v69
	v_cvt_pk_bf16_f32 v67, v71, v67
	global_store_dwordx4 v[88:89], v[64:67], off
	s_nop 1
	v_mov_b64_e32 v[64:65], v[198:199]
	v_mov_b64_e32 v[66:67], v[200:201]
	s_nop 0
	v_mov_b64_e32 v[68:69], v[202:203]
	v_mov_b64_e32 v[70:71], v[204:205]
	v_lshl_add_u64 v[80:81], v[136:137], 0, s[10:11]
	v_pk_mul_f32 v[54:55], v[66:67], v[54:55]
	v_pk_mul_f32 v[52:53], v[64:65], v[52:53]
	v_pk_mul_f32 v[50:51], v[70:71], v[50:51]
	v_pk_mul_f32 v[48:49], v[68:69], v[48:49]
	v_pk_fma_f32 v[54:55], v[82:83], v[54:55], v[62:63] op_sel_hi:[0,1,1]
	v_pk_fma_f32 v[52:53], v[82:83], v[52:53], v[60:61] op_sel_hi:[0,1,1]
	v_pk_fma_f32 v[50:51], v[82:83], v[50:51], v[58:59] op_sel_hi:[0,1,1]
	v_pk_fma_f32 v[48:49], v[82:83], v[48:49], v[56:57] op_sel_hi:[0,1,1]
	v_mul_f32_e32 v48, 0xbfb8aa3b, v48
	v_mul_f32_e32 v53, 0xbfb8aa3b, v53
	v_mul_f32_e32 v49, 0xbfb8aa3b, v49
	v_mul_f32_e32 v54, 0xbfb8aa3b, v54
	v_mul_f32_e32 v51, 0xbfb8aa3b, v51
	v_mul_f32_e32 v52, 0xbfb8aa3b, v52
	v_mul_f32_e32 v50, 0xbfb8aa3b, v50
	v_mul_f32_e32 v55, 0xbfb8aa3b, v55
	v_exp_f32_e32 v48, v48
	v_exp_f32_e32 v53, v53
	v_exp_f32_e32 v49, v49
	v_exp_f32_e32 v54, v54
	v_exp_f32_e32 v51, v51
	v_exp_f32_e32 v52, v52
	v_exp_f32_e32 v50, v50
	v_exp_f32_e32 v55, v55
	v_add_f32_e32 v48, 1.0, v48
	v_add_f32_e32 v53, 1.0, v53
	v_add_f32_e32 v49, 1.0, v49
	v_add_f32_e32 v54, 1.0, v54
	v_add_f32_e32 v51, 1.0, v51
	v_add_f32_e32 v52, 1.0, v52
	v_add_f32_e32 v50, 1.0, v50
	v_add_f32_e32 v55, 1.0, v55
	v_rcp_f32_e32 v64, v48
	v_rcp_f32_e32 v48, v53
	v_rcp_f32_e32 v53, v49
	v_rcp_f32_e32 v49, v54
	v_rcp_f32_e32 v51, v51
	v_rcp_f32_e32 v52, v52
	v_rcp_f32_e32 v54, v55
	v_rcp_f32_e32 v55, v50
	v_cvt_pk_bf16_f32 v48, v52, v48
	v_cvt_pk_bf16_f32 v49, v49, v54
	v_cvt_pk_bf16_f32 v50, v64, v53
	v_cvt_pk_bf16_f32 v51, v55, v51
	global_store_dwordx4 v[80:81], v[48:51], off offset:256
	s_nop 1
	v_mov_b32_e32 v66, v210
	s_nop 0
	v_mov_b64_e32 v[48:49], v[190:191]
	v_mov_b64_e32 v[50:51], v[192:193]
	v_mov_b64_e32 v[52:53], v[194:195]
	v_mov_b64_e32 v[54:55], v[196:197]
	v_add_co_u32_e32 v64, vcc, s51, v136
	v_fmamk_f32 v66, v66, 0x3a000000, v172
	v_pk_mul_f32 v[46:47], v[50:51], v[46:47]
	v_rsq_f32_e32 v50, v66
	v_pk_mul_f32 v[44:45], v[48:49], v[44:45]
	v_pk_mul_f32 v[42:43], v[54:55], v[42:43]
	v_pk_mul_f32 v[40:41], v[52:53], v[40:41]
	v_pk_fma_f32 v[46:47], v[46:47], v[50:51], v[78:79] op_sel_hi:[1,0,1]
	v_pk_fma_f32 v[44:45], v[44:45], v[50:51], v[76:77] op_sel_hi:[1,0,1]
	v_pk_fma_f32 v[42:43], v[42:43], v[50:51], v[74:75] op_sel_hi:[1,0,1]
	v_pk_fma_f32 v[40:41], v[40:41], v[50:51], v[72:73] op_sel_hi:[1,0,1]
	v_mul_f32_e32 v45, 0xbfb8aa3b, v45
	v_mul_f32_e32 v40, 0xbfb8aa3b, v40
	v_mul_f32_e32 v41, 0xbfb8aa3b, v41
	v_mul_f32_e32 v46, 0xbfb8aa3b, v46
	v_mul_f32_e32 v43, 0xbfb8aa3b, v43
	v_mul_f32_e32 v44, 0xbfb8aa3b, v44
	v_mul_f32_e32 v42, 0xbfb8aa3b, v42
	v_mul_f32_e32 v47, 0xbfb8aa3b, v47
	v_exp_f32_e32 v40, v40
	v_exp_f32_e32 v45, v45
	v_exp_f32_e32 v41, v41
	v_exp_f32_e32 v46, v46
	v_exp_f32_e32 v43, v43
	v_exp_f32_e32 v44, v44
	v_exp_f32_e32 v42, v42
	v_exp_f32_e32 v47, v47
	v_add_f32_e32 v40, 1.0, v40
	v_add_f32_e32 v45, 1.0, v45
	v_add_f32_e32 v41, 1.0, v41
	v_add_f32_e32 v46, 1.0, v46
	v_add_f32_e32 v43, 1.0, v43
	v_addc_co_u32_e32 v65, vcc, 0, v137, vcc
	v_add_f32_e32 v44, 1.0, v44
; __device__ __forceinline__ unsigned cvt_pk_bf16(float lo, float hi) { unsigned r; asm volatile("v_cvt_pk_bf16_f32 %0, %1, %2" : "=v"(r) : "v"(lo), "v"(hi)); return r; }
; __device__ __forceinline__ float ld_agent(const float* p) { return __hip_atomic_load(p, __ATOMIC_RELAXED, __HIP_MEMORY_SCOPE_AGENT); }
; __device__ __forceinline__ float rs_of(const float* ssq, int r) { return __builtin_amdgcn_rsqf(ld_agent(ssq + r) * (1.f / 2048.f) + EPS); }
; __device__ __forceinline__ float sigm(float x) { return __builtin_amdgcn_rcpf(1.f + __builtin_amdgcn_exp2f(-LOG2E * x)); }
;     __device__ __forceinline__ void operator()(const i32x4 (&acc)[2][2][4][2], const Unit& u, int wr, int wc, int fr, int fq) const {
;     ...
;         for (int ai = 0; ai < 2; ++ai)
; #pragma unroll
;             for (int m = 0; m < 4; ++m) {
;                 const int r = row0 + ai * HALF + m * 16; const float rs = rs_of(ssq, r);
;                 bf16_t* rowp = O + (size_t)r * ldc + col0;
; #pragma unroll
;                 for (int bj = 0; bj < 2; ++bj) {
;                     const f32x4 s0 = *(const f32x4*)(swp + col0 + bj * HALF), s1 = *(const f32x4*)(swp + col0 + bj * HALF + 4);
;                     f32x4 v0 = __builtin_convertvector(acc[ai][bj][m][0], f32x4) * s0 * rs + bv[bj][0], v1 = __builtin_convertvector(acc[ai][bj][m][1], f32x4) * s1 * rs + bv[bj][1];
; #pragma unroll
;                     for (int j = 0; j < 4; ++j) { v0[j] = sigm(v0[j]); v1[j] = sigm(v1[j]); }
;                     u32x4 w; w.x = cvt_pk_bf16(v0[0], v0[1]); w.y = cvt_pk_bf16(v0[2], v0[3]); w.z = cvt_pk_bf16(v1[0], v1[1]); w.w = cvt_pk_bf16(v1[2], v1[3]);
;                     *(u32x4*)(rowp + bj * HALF) = w;
;                 }
;             }
	v_add_f32_e32 v42, 1.0, v42
	v_add_f32_e32 v47, 1.0, v47
	v_rcp_f32_e32 v48, v40
	v_rcp_f32_e32 v40, v45
	v_rcp_f32_e32 v45, v41
	v_rcp_f32_e32 v41, v46
	v_rcp_f32_e32 v43, v43
	v_rcp_f32_e32 v44, v44
	v_rcp_f32_e32 v46, v47
	v_rcp_f32_e32 v47, v42
	v_cvt_pk_bf16_f32 v40, v44, v40
	v_cvt_pk_bf16_f32 v41, v41, v46
	v_cvt_pk_bf16_f32 v42, v48, v45
	v_cvt_pk_bf16_f32 v43, v47, v43
	global_store_dwordx4 v[64:65], v[40:43], off
	s_nop 1
	v_mov_b64_e32 v[40:41], v[198:199]
	v_mov_b64_e32 v[42:43], v[200:201]
	s_nop 0
	v_mov_b64_e32 v[44:45], v[202:203]
	v_mov_b64_e32 v[46:47], v[204:205]
	v_lshl_add_u64 v[48:49], v[136:137], 0, s[12:13]
	v_pk_mul_f32 v[38:39], v[42:43], v[38:39]
	v_pk_mul_f32 v[36:37], v[40:41], v[36:37]
	v_pk_mul_f32 v[34:35], v[46:47], v[34:35]
	v_pk_mul_f32 v[32:33], v[44:45], v[32:33]
	v_pk_fma_f32 v[38:39], v[50:51], v[38:39], v[62:63] op_sel_hi:[0,1,1]
	v_pk_fma_f32 v[36:37], v[50:51], v[36:37], v[60:61] op_sel_hi:[0,1,1]
	v_pk_fma_f32 v[34:35], v[50:51], v[34:35], v[58:59] op_sel_hi:[0,1,1]
	v_pk_fma_f32 v[32:33], v[50:51], v[32:33], v[56:57] op_sel_hi:[0,1,1]
	v_mul_f32_e32 v32, 0xbfb8aa3b, v32
	v_mul_f32_e32 v37, 0xbfb8aa3b, v37
	v_mul_f32_e32 v33, 0xbfb8aa3b, v33
	v_mul_f32_e32 v38, 0xbfb8aa3b, v38
	v_mul_f32_e32 v35, 0xbfb8aa3b, v35
	v_mul_f32_e32 v36, 0xbfb8aa3b, v36
	v_mul_f32_e32 v34, 0xbfb8aa3b, v34
	v_mul_f32_e32 v39, 0xbfb8aa3b, v39
	v_exp_f32_e32 v32, v32
	v_exp_f32_e32 v37, v37
	v_exp_f32_e32 v33, v33
	v_exp_f32_e32 v38, v38
	v_exp_f32_e32 v35, v35
	v_exp_f32_e32 v36, v36
	v_exp_f32_e32 v34, v34
	v_exp_f32_e32 v39, v39
	v_add_f32_e32 v32, 1.0, v32
	v_add_f32_e32 v37, 1.0, v37
	v_add_f32_e32 v33, 1.0, v33
	v_add_f32_e32 v38, 1.0, v38
	v_add_f32_e32 v35, 1.0, v35
	v_add_f32_e32 v36, 1.0, v36
	v_add_f32_e32 v34, 1.0, v34
	v_add_f32_e32 v39, 1.0, v39
	v_rcp_f32_e32 v40, v32
	v_rcp_f32_e32 v32, v37
	v_rcp_f32_e32 v37, v33
	v_rcp_f32_e32 v33, v38
	v_rcp_f32_e32 v35, v35
	v_rcp_f32_e32 v36, v36
	v_rcp_f32_e32 v38, v39
	v_rcp_f32_e32 v39, v34
	v_cvt_pk_bf16_f32 v32, v36, v32
	v_cvt_pk_bf16_f32 v33, v33, v38
	v_cvt_pk_bf16_f32 v34, v40, v37
	v_cvt_pk_bf16_f32 v35, v39, v35
	global_store_dwordx4 v[48:49], v[32:35], off offset:256
	s_nop 1
	v_mov_b32_e32 v42, v211
	s_nop 0
	v_mov_b64_e32 v[32:33], v[190:191]
	v_mov_b64_e32 v[34:35], v[192:193]
	v_mov_b64_e32 v[36:37], v[194:195]
	v_mov_b64_e32 v[38:39], v[196:197]
	v_add_co_u32_e32 v40, vcc, s52, v136
	v_fmamk_f32 v42, v42, 0x3a000000, v172
	v_pk_mul_f32 v[30:31], v[34:35], v[30:31]
	v_rsq_f32_e32 v34, v42
	v_pk_mul_f32 v[28:29], v[32:33], v[28:29]
	v_pk_mul_f32 v[26:27], v[38:39], v[26:27]
	v_pk_mul_f32 v[24:25], v[36:37], v[24:25]
	v_pk_fma_f32 v[30:31], v[30:31], v[34:35], v[78:79] op_sel_hi:[1,0,1]
	v_pk_fma_f32 v[28:29], v[28:29], v[34:35], v[76:77] op_sel_hi:[1,0,1]
	v_pk_fma_f32 v[26:27], v[26:27], v[34:35], v[74:75] op_sel_hi:[1,0,1]
	v_pk_fma_f32 v[24:25], v[24:25], v[34:35], v[72:73] op_sel_hi:[1,0,1]
	v_mul_f32_e32 v29, 0xbfb8aa3b, v29
	v_mul_f32_e32 v24, 0xbfb8aa3b, v24
	v_mul_f32_e32 v25, 0xbfb8aa3b, v25
	v_mul_f32_e32 v30, 0xbfb8aa3b, v30
	v_mul_f32_e32 v27, 0xbfb8aa3b, v27
	v_mul_f32_e32 v28, 0xbfb8aa3b, v28
	v_mul_f32_e32 v26, 0xbfb8aa3b, v26
	v_mul_f32_e32 v31, 0xbfb8aa3b, v31
	v_exp_f32_e32 v24, v24
	v_exp_f32_e32 v29, v29
	v_exp_f32_e32 v25, v25
	v_exp_f32_e32 v30, v30
	v_exp_f32_e32 v27, v27
	v_exp_f32_e32 v28, v28
	v_exp_f32_e32 v26, v26
	v_exp_f32_e32 v31, v31
	v_add_f32_e32 v24, 1.0, v24
	v_add_f32_e32 v29, 1.0, v29
	v_add_f32_e32 v25, 1.0, v25
	v_add_f32_e32 v30, 1.0, v30
	v_add_f32_e32 v27, 1.0, v27
	v_addc_co_u32_e32 v41, vcc, 0, v137, vcc
	v_add_f32_e32 v28, 1.0, v28
	v_add_f32_e32 v26, 1.0, v26
	v_add_f32_e32 v31, 1.0, v31
	v_rcp_f32_e32 v32, v24
	v_rcp_f32_e32 v24, v29
	v_rcp_f32_e32 v29, v25
	v_rcp_f32_e32 v25, v30
	v_rcp_f32_e32 v27, v27
	v_rcp_f32_e32 v28, v28
	v_rcp_f32_e32 v30, v31
	v_rcp_f32_e32 v31, v26
	v_cvt_pk_bf16_f32 v24, v28, v24
	v_cvt_pk_bf16_f32 v25, v25, v30
	v_cvt_pk_bf16_f32 v26, v32, v29
	v_cvt_pk_bf16_f32 v27, v31, v27
	global_store_dwordx4 v[40:41], v[24:27], off
	s_nop 1
	v_mov_b64_e32 v[24:25], v[198:199]
	v_mov_b64_e32 v[26:27], v[200:201]
	s_nop 0
	v_mov_b64_e32 v[28:29], v[202:203]
	v_mov_b64_e32 v[30:31], v[204:205]
	v_lshl_add_u64 v[32:33], v[136:137], 0, s[14:15]
	v_pk_mul_f32 v[22:23], v[26:27], v[22:23]
	v_pk_mul_f32 v[20:21], v[24:25], v[20:21]
	v_pk_mul_f32 v[18:19], v[30:31], v[18:19]
	v_pk_mul_f32 v[16:17], v[28:29], v[16:17]
	v_pk_fma_f32 v[22:23], v[34:35], v[22:23], v[62:63] op_sel_hi:[0,1,1]
	v_pk_fma_f32 v[20:21], v[34:35], v[20:21], v[60:61] op_sel_hi:[0,1,1]
	v_pk_fma_f32 v[18:19], v[34:35], v[18:19], v[58:59] op_sel_hi:[0,1,1]
	v_pk_fma_f32 v[16:17], v[34:35], v[16:17], v[56:57] op_sel_hi:[0,1,1]
; __device__ __forceinline__ unsigned cvt_pk_bf16(float lo, float hi) { unsigned r; asm volatile("v_cvt_pk_bf16_f32 %0, %1, %2" : "=v"(r) : "v"(lo), "v"(hi)); return r; }
; __device__ __forceinline__ float rs_of(const float* ssq, int r) { return __builtin_amdgcn_rsqf(ld_agent(ssq + r) * (1.f / 2048.f) + EPS); }
; __device__ __forceinline__ float sigm(float x) { return __builtin_amdgcn_rcpf(1.f + __builtin_amdgcn_exp2f(-LOG2E * x)); }
;     __device__ __forceinline__ void operator()(const i32x4 (&acc)[2][2][4][2], const Unit& u, int wr, int wc, int fr, int fq) const {
;     ...
;         for (int ai = 0; ai < 2; ++ai)
; #pragma unroll
;             for (int m = 0; m < 4; ++m) {
;                 const int r = row0 + ai * HALF + m * 16; const float rs = rs_of(ssq, r);
;                 bf16_t* rowp = O + (size_t)r * ldc + col0;
; #pragma unroll
;                 for (int bj = 0; bj < 2; ++bj) {
;                     const f32x4 s0 = *(const f32x4*)(swp + col0 + bj * HALF), s1 = *(const f32x4*)(swp + col0 + bj * HALF + 4);
;                     f32x4 v0 = __builtin_convertvector(acc[ai][bj][m][0], f32x4) * s0 * rs + bv[bj][0], v1 = __builtin_convertvector(acc[ai][bj][m][1], f32x4) * s1 * rs + bv[bj][1];
; #pragma unroll
;                     for (int j = 0; j < 4; ++j) { v0[j] = sigm(v0[j]); v1[j] = sigm(v1[j]); }
;                     u32x4 w; w.x = cvt_pk_bf16(v0[0], v0[1]); w.y = cvt_pk_bf16(v0[2], v0[3]); w.z = cvt_pk_bf16(v1[0], v1[1]); w.w = cvt_pk_bf16(v1[2], v1[3]);
;                     *(u32x4*)(rowp + bj * HALF) = w;
;                 }
;             }
; template <class Epi, class Sched>
; __device__ __forceinline__ void gemm_phase(LAS unsigned char* lds, const Gemm g, const Sched& S, const Epi& E) {
;     ...
;         E(acc, cur, wr, wc, fr, fq);
;         if (!has_next) break;
	v_mul_f32_e32 v16, 0xbfb8aa3b, v16
	v_mul_f32_e32 v21, 0xbfb8aa3b, v21
	v_mul_f32_e32 v17, 0xbfb8aa3b, v17
	v_mul_f32_e32 v22, 0xbfb8aa3b, v22
	v_mul_f32_e32 v19, 0xbfb8aa3b, v19
	v_mul_f32_e32 v20, 0xbfb8aa3b, v20
	v_mul_f32_e32 v18, 0xbfb8aa3b, v18
	v_mul_f32_e32 v23, 0xbfb8aa3b, v23
	v_exp_f32_e32 v16, v16
	v_exp_f32_e32 v21, v21
	v_exp_f32_e32 v17, v17
	v_exp_f32_e32 v22, v22
	v_exp_f32_e32 v19, v19
	v_exp_f32_e32 v20, v20
	v_exp_f32_e32 v18, v18
	v_exp_f32_e32 v23, v23
	v_add_f32_e32 v16, 1.0, v16
	v_add_f32_e32 v21, 1.0, v21
	v_add_f32_e32 v17, 1.0, v17
	v_add_f32_e32 v22, 1.0, v22
	v_add_f32_e32 v19, 1.0, v19
	v_add_f32_e32 v20, 1.0, v20
	v_add_f32_e32 v18, 1.0, v18
	v_add_f32_e32 v23, 1.0, v23
	v_rcp_f32_e32 v24, v16
	v_rcp_f32_e32 v16, v21
	v_rcp_f32_e32 v21, v17
	v_rcp_f32_e32 v17, v22
	v_rcp_f32_e32 v19, v19
	v_rcp_f32_e32 v20, v20
	v_rcp_f32_e32 v22, v23
	v_rcp_f32_e32 v23, v18
	v_cvt_pk_bf16_f32 v16, v20, v16
	v_cvt_pk_bf16_f32 v17, v17, v22
	v_cvt_pk_bf16_f32 v18, v24, v21
	v_cvt_pk_bf16_f32 v19, v23, v19
	global_store_dwordx4 v[32:33], v[16:19], off offset:256
	s_nop 1
	v_mov_b32_e32 v26, v212
	s_nop 0
	v_mov_b64_e32 v[16:17], v[190:191]
	v_mov_b64_e32 v[18:19], v[192:193]
	v_mov_b64_e32 v[20:21], v[194:195]
	v_mov_b64_e32 v[22:23], v[196:197]
	v_add_co_u32_e32 v24, vcc, s53, v136
	v_fmamk_f32 v26, v26, 0x3a000000, v172
	v_pk_mul_f32 v[14:15], v[18:19], v[14:15]
	v_rsq_f32_e32 v18, v26
	v_pk_mul_f32 v[12:13], v[16:17], v[12:13]
	v_pk_mul_f32 v[10:11], v[22:23], v[10:11]
	v_pk_mul_f32 v[8:9], v[20:21], v[8:9]
	v_pk_fma_f32 v[14:15], v[14:15], v[18:19], v[78:79] op_sel_hi:[1,0,1]
	v_pk_fma_f32 v[12:13], v[12:13], v[18:19], v[76:77] op_sel_hi:[1,0,1]
	v_pk_fma_f32 v[10:11], v[10:11], v[18:19], v[74:75] op_sel_hi:[1,0,1]
	v_pk_fma_f32 v[8:9], v[8:9], v[18:19], v[72:73] op_sel_hi:[1,0,1]
	v_mul_f32_e32 v13, 0xbfb8aa3b, v13
	v_mul_f32_e32 v8, 0xbfb8aa3b, v8
	v_mul_f32_e32 v9, 0xbfb8aa3b, v9
	v_mul_f32_e32 v14, 0xbfb8aa3b, v14
	v_mul_f32_e32 v11, 0xbfb8aa3b, v11
	v_mul_f32_e32 v12, 0xbfb8aa3b, v12
	v_mul_f32_e32 v10, 0xbfb8aa3b, v10
	v_mul_f32_e32 v15, 0xbfb8aa3b, v15
	v_exp_f32_e32 v8, v8
	v_exp_f32_e32 v13, v13
	v_exp_f32_e32 v9, v9
	v_exp_f32_e32 v14, v14
	v_exp_f32_e32 v11, v11
	v_exp_f32_e32 v12, v12
	v_exp_f32_e32 v10, v10
	v_exp_f32_e32 v15, v15
	v_add_f32_e32 v8, 1.0, v8
	v_add_f32_e32 v13, 1.0, v13
	v_add_f32_e32 v9, 1.0, v9
	v_add_f32_e32 v14, 1.0, v14
	v_add_f32_e32 v11, 1.0, v11
	v_addc_co_u32_e32 v25, vcc, 0, v137, vcc
	v_add_f32_e32 v12, 1.0, v12
	v_add_f32_e32 v10, 1.0, v10
	v_add_f32_e32 v15, 1.0, v15
	v_rcp_f32_e32 v16, v8
	v_rcp_f32_e32 v8, v13
	v_rcp_f32_e32 v13, v9
	v_rcp_f32_e32 v9, v14
	v_rcp_f32_e32 v11, v11
	v_rcp_f32_e32 v12, v12
	v_rcp_f32_e32 v14, v15
	v_rcp_f32_e32 v15, v10
	v_cvt_pk_bf16_f32 v8, v12, v8
	v_cvt_pk_bf16_f32 v9, v9, v14
	v_cvt_pk_bf16_f32 v10, v16, v13
	v_cvt_pk_bf16_f32 v11, v15, v11
	global_store_dwordx4 v[24:25], v[8:11], off
	s_nop 1
	v_mov_b64_e32 v[8:9], v[198:199]
	v_mov_b64_e32 v[10:11], v[200:201]
	s_nop 0
	v_mov_b64_e32 v[12:13], v[202:203]
	v_mov_b64_e32 v[14:15], v[204:205]
	s_and_b64 vcc, exec, s[0:1]
	v_lshl_add_u64 v[16:17], v[136:137], 0, s[16:17]
	v_pk_mul_f32 v[6:7], v[10:11], v[6:7]
	v_pk_mul_f32 v[4:5], v[8:9], v[4:5]
	v_pk_mul_f32 v[2:3], v[14:15], v[2:3]
	v_pk_mul_f32 v[0:1], v[12:13], v[0:1]
	v_pk_fma_f32 v[6:7], v[18:19], v[6:7], v[62:63] op_sel_hi:[0,1,1]
	v_pk_fma_f32 v[4:5], v[18:19], v[4:5], v[60:61] op_sel_hi:[0,1,1]
	v_pk_fma_f32 v[2:3], v[18:19], v[2:3], v[58:59] op_sel_hi:[0,1,1]
	v_pk_fma_f32 v[0:1], v[18:19], v[0:1], v[56:57] op_sel_hi:[0,1,1]
	v_mul_f32_e32 v0, 0xbfb8aa3b, v0
	v_mul_f32_e32 v5, 0xbfb8aa3b, v5
	v_mul_f32_e32 v1, 0xbfb8aa3b, v1
	v_mul_f32_e32 v6, 0xbfb8aa3b, v6
	v_mul_f32_e32 v3, 0xbfb8aa3b, v3
	v_mul_f32_e32 v4, 0xbfb8aa3b, v4
	v_mul_f32_e32 v2, 0xbfb8aa3b, v2
	v_mul_f32_e32 v7, 0xbfb8aa3b, v7
	v_exp_f32_e32 v0, v0
	v_exp_f32_e32 v5, v5
	v_exp_f32_e32 v1, v1
	v_exp_f32_e32 v6, v6
	v_exp_f32_e32 v3, v3
	v_exp_f32_e32 v4, v4
	v_exp_f32_e32 v2, v2
	v_exp_f32_e32 v7, v7
	v_add_f32_e32 v0, 1.0, v0
	v_add_f32_e32 v5, 1.0, v5
	v_add_f32_e32 v1, 1.0, v1
	v_add_f32_e32 v6, 1.0, v6
	v_add_f32_e32 v3, 1.0, v3
	v_add_f32_e32 v4, 1.0, v4
	v_add_f32_e32 v2, 1.0, v2
	v_add_f32_e32 v7, 1.0, v7
	v_rcp_f32_e32 v8, v0
	v_rcp_f32_e32 v0, v5
	v_rcp_f32_e32 v5, v1
	v_rcp_f32_e32 v1, v6
	v_rcp_f32_e32 v3, v3
	v_rcp_f32_e32 v4, v4
	v_rcp_f32_e32 v6, v7
	v_rcp_f32_e32 v7, v2
	v_cvt_pk_bf16_f32 v0, v4, v0
	v_cvt_pk_bf16_f32 v1, v1, v6
	v_cvt_pk_bf16_f32 v2, v8, v5
	v_cvt_pk_bf16_f32 v3, v7, v3
	global_store_dwordx4 v[16:17], v[0:3], off offset:256
	s_nop 1
	s_cbranch_vccz .LBB0_632
	s_waitcnt vmcnt(0)
	s_cmpk_gt_u32 s33, 0xff
	s_cbranch_scc1 .LBB0_639
	s_barrier
